# speedup vs baseline: 1.0041x; 1.0041x over previous
; __device__ __forceinline__ int tid_fresh() { int t = (int)threadIdx.x; asm volatile("" : "+v"(t)); return t; }
; __device__ __forceinline__ void conv_phase(const bf16_t* Z, bf16_t* UA, const float* cw, const float* cb, int nrows, int rowoff) {
;     const int gtid = blockIdx.x * 512 + tid_fresh(), NT = gridDim.x * 512; const int total = (nrows / 16) * 352;
;     for (int idx = gtid; idx < total; idx += NT) {
;         const int cgp = idx % 352, rb = idx / 352, c0 = cgp * 8, r0 = rb * 16, grow0 = rowoff + r0;
;         const int seg = grow0 < MLAT ? SEQ : CTXL; const bool has_left = (grow0 & (seg - 1)) != 0, has_right = ((grow0 + 16) & (seg - 1)) != 0;
;         float wa[3][8], wg[3][8], ba[8], bg[8];
; #pragma unroll
;         for (int j = 0; j < 3; ++j)
; #pragma unroll
;             for (int h = 0; h < 2; ++h) { const f32x4 x = *(const f32x4*)(cw + j * FFN2 + c0 + 4 * h), y = *(const f32x4*)(cw + j * FFN2 + FFN + c0 + 4 * h);
; #pragma unroll
;                 for (int e = 0; e < 4; ++e) { wa[j][4 * h + e] = x[e]; wg[j][4 * h + e] = y[e]; } }
; #pragma unroll
;         for (int h = 0; h < 2; ++h) { const f32x4 x = *(const f32x4*)(cb + c0 + 4 * h), y = *(const f32x4*)(cb + FFN + c0 + 4 * h);
; #pragma unroll
;             for (int e = 0; e < 4; ++e) { ba[4 * h + e] = x[e]; bg[4 * h + e] = y[e]; } }
;         const bf16_t* zp = Z + (size_t)r0 * FFN2 + c0; const u32x4 zero = (u32x4){0u, 0u, 0u, 0u};
;         u32x4 pa = zero, pg = zero; if (has_left) { pa = *(const u32x4*)(zp - FFN2); pg = *(const u32x4*)(zp - FFN2 + FFN); }
;         u32x4 ca = *(const u32x4*)(zp), cgv = *(const u32x4*)(zp + FFN);
; #pragma unroll 4
;         for (int rr = 0; rr < 16; ++rr) {
;             u32x4 na = zero, ng = zero; if (rr < 15 || has_right) { na = *(const u32x4*)(zp + (size_t)(rr + 1) * FFN2); ng = *(const u32x4*)(zp + (size_t)(rr + 1) * FFN2 + FFN); }
;             u32x4 o;
; #pragma unroll
;             for (int e2 = 0; e2 < 4; ++e2) {
;                 const float a0 = bflo(pa[e2]) * wa[0][2 * e2] + bflo(ca[e2]) * wa[1][2 * e2] + bflo(na[e2]) * wa[2][2 * e2] + ba[2 * e2];
;                 const float a1 = bfhi(pa[e2]) * wa[0][2 * e2 + 1] + bfhi(ca[e2]) * wa[1][2 * e2 + 1] + bfhi(na[e2]) * wa[2][2 * e2 + 1] + ba[2 * e2 + 1];
;                 const float g0 = bflo(pg[e2]) * wg[0][2 * e2] + bflo(cgv[e2]) * wg[1][2 * e2] + bflo(ng[e2]) * wg[2][2 * e2] + bg[2 * e2];
.LBB0_459:
	s_or_b64 exec, exec, s[2:3]
	v_mov_b32_e32 v1, v204
	v_readlane_b32 s2, v255, 17
	s_lshr_b32 s12, s45, 4
	s_waitcnt lgkmcnt(0)
	s_barrier
	s_mulk_i32 s12, 0x160
	s_xor_b64 s[88:89], s[40:41], -1
	v_readlane_b32 s2, v254, 21
	v_readlane_b32 s3, v254, 22
	v_readlane_b32 s98, v255, 17
	s_load_dwordx2 s[38:39], s[2:3], 0x98
	s_load_dwordx2 s[40:41], s[2:3], 0xa0
	s_add_u32 s36, s54, 0x23a00000
	s_addc_u32 s37, s55, 0
	v_mov_b32_e32 v180, 0xbfb8aa3b
	v_mov_b32_e32 v181, 0xbfb8aa3b
	v_mov_b32_e32 v144, 1.0
	v_mov_b32_e32 v145, 1.0
	v_add_u32_e32 v1, s98, v204
	s_mov_b32 s99, 0x2e8ba2e9
	v_mul_hi_u32 v2, v1, s99
	v_lshrrev_b32_e32 v2, 6, v2
	v_mul_u32_u24_e32 v3, 0x160, v2
	v_sub_u32_e32 v3, v1, v3
	v_lshlrev_b32_e32 v4, 5, v3
	v_mul_u32_u24_e32 v5, 180224, v2
	v_lshl_add_u32 v5, v3, 4, v5
	v_mul_u32_u24_e32 v6, 90112, v2
	v_lshl_add_u32 v6, v3, 4, v6
	s_lshr_b32 s99, s43, 4
	v_add_u32_e32 v7, s99, v2
	s_waitcnt lgkmcnt(0)
	s_sub_u32 s2, s64, 0x4000
	s_subb_u32 s3, s65, 0
	s_mov_b32 s98, 0
	s_mov_b32 s99, 0xffff0000
	global_load_dwordx4 v[152:155], v4, s[38:39]
	global_load_dwordx4 v[156:159], v4, s[38:39] offset:16
	v_add_u32_e32 v10, 11264, v4
	global_load_dwordx4 v[212:215], v10, s[38:39]
	global_load_dwordx4 v[216:219], v10, s[38:39] offset:16
	v_add_u32_e32 v11, 22528, v4
	global_load_dwordx4 v[160:163], v11, s[38:39]
	global_load_dwordx4 v[164:167], v11, s[38:39] offset:16
	v_add_u32_e32 v10, 33792, v4
	global_load_dwordx4 v[220:223], v10, s[38:39]
	global_load_dwordx4 v[224:227], v10, s[38:39] offset:16
	v_add_u32_e32 v11, 45056, v4
	global_load_dwordx4 v[168:171], v11, s[38:39]
	global_load_dwordx4 v[172:175], v11, s[38:39] offset:16
	v_add_u32_e32 v10, 56320, v4
	global_load_dwordx4 v[228:231], v10, s[38:39]
	global_load_dwordx4 v[232:235], v10, s[38:39] offset:16
	global_load_dwordx4 v[236:239], v4, s[40:41]
	global_load_dwordx4 v[240:243], v4, s[40:41] offset:16
	v_add_u32_e32 v11, 11264, v4
	global_load_dwordx4 v[244:247], v11, s[40:41]
	global_load_dwordx4 v[248:251], v11, s[40:41] offset:16
	v_add_u32_e32 v10, 7936, v5
	global_load_dwordx4 v[64:67], v10, s[2:3] offset:-2816
	global_load_dwordx4 v[68:71], v10, s[2:3] offset:2816
	global_load_dword v252, v4, s[40:41]
	v_add_u32_e32 v11, 19200, v5
	global_load_dwordx4 v[72:75], v11, s[2:3] offset:-2816
	global_load_dwordx4 v[76:79], v11, s[2:3] offset:2816
	global_load_dword v252, v4, s[40:41]
	v_add_u32_e32 v10, 30464, v5
	global_load_dwordx4 v[80:83], v10, s[2:3] offset:-2816
	global_load_dwordx4 v[84:87], v10, s[2:3] offset:2816
	global_load_dword v252, v4, s[40:41]
	v_add_u32_e32 v11, 41728, v5
	global_load_dwordx4 v[88:91], v11, s[2:3] offset:-2816
	global_load_dwordx4 v[92:95], v11, s[2:3] offset:2816
	global_load_dword v252, v4, s[40:41]
	v_add_u32_e32 v10, 52992, v5
	global_load_dwordx4 v[96:99], v10, s[2:3] offset:-2816
	global_load_dwordx4 v[100:103], v10, s[2:3] offset:2816
	global_load_dword v252, v4, s[40:41]
	v_add_u32_e32 v11, 64256, v5
	global_load_dwordx4 v[104:107], v11, s[2:3] offset:-2816
	global_load_dwordx4 v[108:111], v11, s[2:3] offset:2816
	global_load_dword v252, v4, s[40:41]
	v_add_u32_e32 v10, 75520, v5
	global_load_dwordx4 v[112:115], v10, s[2:3] offset:-2816
	global_load_dwordx4 v[116:119], v10, s[2:3] offset:2816
	global_load_dword v252, v4, s[40:41]
	v_add_u32_e32 v11, 86784, v5
	global_load_dwordx4 v[120:123], v11, s[2:3] offset:-2816
	global_load_dwordx4 v[124:127], v11, s[2:3] offset:2816
	global_load_dword v252, v4, s[40:41]
	v_add_u32_e32 v10, 98048, v5
	global_load_dwordx4 v[128:131], v10, s[2:3] offset:-2816
	global_load_dwordx4 v[132:135], v10, s[2:3] offset:2816
	global_load_dword v252, v4, s[40:41]
.Lconv_item_l0:
	v_mov_b32_e32 v9, 0x1ff
	v_cmp_gt_u32_e32 vcc, 0x1000, v7
	s_nop 1
	v_cndmask_b32_e32 v8, 15, v9, vcc
	v_and_b32_e32 v9, v7, v8
	v_cmp_ne_u32_e64 s[60:61], 0, v9
	v_add_u32_e32 v9, 1, v7
	v_and_b32_e32 v9, v9, v8
	v_cmp_ne_u32_e64 s[100:101], 0, v9
	s_waitcnt vmcnt(25)
	v_cndmask_b32_e64 v64, 0, v64, s[60:61]
	v_cndmask_b32_e64 v65, 0, v65, s[60:61]
	v_cndmask_b32_e64 v66, 0, v66, s[60:61]
	v_cndmask_b32_e64 v67, 0, v67, s[60:61]
	v_cndmask_b32_e64 v68, 0, v68, s[60:61]
	v_cndmask_b32_e64 v69, 0, v69, s[60:61]
	v_cndmask_b32_e64 v70, 0, v70, s[60:61]
	v_cndmask_b32_e64 v71, 0, v71, s[60:61]
	v_lshlrev_b32_e32 v16, 16, v64
	v_and_b32_e32 v17, s99, v64
	v_lshlrev_b32_e32 v18, 16, v65
	v_and_b32_e32 v19, s99, v65
	v_lshlrev_b32_e32 v20, 16, v66
	v_and_b32_e32 v21, s99, v66
	v_lshlrev_b32_e32 v22, 16, v67
	v_and_b32_e32 v23, s99, v67
	v_lshlrev_b32_e32 v24, 16, v68
	v_and_b32_e32 v25, s99, v68
	v_lshlrev_b32_e32 v26, 16, v69
	v_and_b32_e32 v27, s99, v69
	v_lshlrev_b32_e32 v28, 16, v70
	v_and_b32_e32 v29, s99, v70
	v_lshlrev_b32_e32 v30, 16, v71
	v_and_b32_e32 v31, s99, v71
	v_add_u32_e32 v11, 109312, v5
	global_load_dwordx4 v[64:67], v11, s[2:3] offset:-2816
	global_load_dwordx4 v[68:71], v11, s[2:3] offset:2816
	s_waitcnt vmcnt(24)
	v_lshlrev_b32_e32 v32, 16, v72
	v_and_b32_e32 v33, s99, v72
	v_lshlrev_b32_e32 v34, 16, v73
	v_and_b32_e32 v35, s99, v73
	v_lshlrev_b32_e32 v36, 16, v74
	v_and_b32_e32 v37, s99, v74
	v_lshlrev_b32_e32 v38, 16, v75
	v_and_b32_e32 v39, s99, v75
	v_lshlrev_b32_e32 v40, 16, v76
	v_and_b32_e32 v41, s99, v76
	v_lshlrev_b32_e32 v42, 16, v77
	v_and_b32_e32 v43, s99, v77
	v_lshlrev_b32_e32 v44, 16, v78
	v_and_b32_e32 v45, s99, v78
	v_lshlrev_b32_e32 v46, 16, v79
	v_and_b32_e32 v47, s99, v79
	v_add_u32_e32 v10, 120576, v5
	global_load_dwordx4 v[72:75], v10, s[2:3] offset:-2816
	global_load_dwordx4 v[76:79], v10, s[2:3] offset:2816
	s_waitcnt vmcnt(23)
; __device__ __forceinline__ unsigned cvt_pk_bf16(float lo, float hi) { unsigned r; asm volatile("v_cvt_pk_bf16_f32 %0, %1, %2" : "=v"(r) : "v"(lo), "v"(hi)); return r; }
; __device__ __forceinline__ float silu_f(float x) { return x * __builtin_amdgcn_rcpf(1.0f + __builtin_amdgcn_exp2f(-LOG2E * x)); }
; __device__ __forceinline__ float bflo(unsigned w) { return __uint_as_float(w << 16); }
; __device__ __forceinline__ float bfhi(unsigned w) { return __uint_as_float(w & 0xffff0000u); }
; __device__ __forceinline__ void conv_phase(const bf16_t* Z, bf16_t* UA, const float* cw, const float* cb, int nrows, int rowoff) {
;     ...
;         for (int rr = 0; rr < 16; ++rr) {
;             u32x4 na = zero, ng = zero; if (rr < 15 || has_right) { na = *(const u32x4*)(zp + (size_t)(rr + 1) * FFN2); ng = *(const u32x4*)(zp + (size_t)(rr + 1) * FFN2 + FFN); }
;             u32x4 o;
; #pragma unroll
;             for (int e2 = 0; e2 < 4; ++e2) {
;                 const float a0 = bflo(pa[e2]) * wa[0][2 * e2] + bflo(ca[e2]) * wa[1][2 * e2] + bflo(na[e2]) * wa[2][2 * e2] + ba[2 * e2];
;                 const float a1 = bfhi(pa[e2]) * wa[0][2 * e2 + 1] + bfhi(ca[e2]) * wa[1][2 * e2 + 1] + bfhi(na[e2]) * wa[2][2 * e2 + 1] + ba[2 * e2 + 1];
;                 const float g0 = bflo(pg[e2]) * wg[0][2 * e2] + bflo(cgv[e2]) * wg[1][2 * e2] + bflo(ng[e2]) * wg[2][2 * e2] + bg[2 * e2];
;                 const float g1 = bfhi(pg[e2]) * wg[0][2 * e2 + 1] + bfhi(cgv[e2]) * wg[1][2 * e2 + 1] + bfhi(ng[e2]) * wg[2][2 * e2 + 1] + bg[2 * e2 + 1];
;                 o[e2] = cvt_pk_bf16(silu_f(a0) * g0, silu_f(a1) * g1); }
;             *(u32x4*)(UA + (size_t)(r0 + rr) * FFN + c0) = o;
;             pa = ca; pg = cgv; ca = na; cgv = ng;
	v_lshlrev_b32_e32 v48, 16, v80
	v_and_b32_e32 v49, s99, v80
	v_lshlrev_b32_e32 v50, 16, v81
	v_and_b32_e32 v51, s99, v81
	v_lshlrev_b32_e32 v52, 16, v82
	v_and_b32_e32 v53, s99, v82
	v_lshlrev_b32_e32 v54, 16, v83
	v_and_b32_e32 v55, s99, v83
	v_lshlrev_b32_e32 v56, 16, v84
	v_and_b32_e32 v57, s99, v84
	v_lshlrev_b32_e32 v58, 16, v85
	v_and_b32_e32 v59, s99, v85
	v_lshlrev_b32_e32 v60, 16, v86
	v_and_b32_e32 v61, s99, v86
	v_lshlrev_b32_e32 v62, 16, v87
	v_and_b32_e32 v63, s99, v87
	v_add_u32_e32 v11, 131840, v5
	global_load_dwordx4 v[80:83], v11, s[2:3] offset:-2816
	global_load_dwordx4 v[84:87], v11, s[2:3] offset:2816
	v_pk_fma_f32 v[136:137], v[16:17], v[152:153], v[236:237]
	v_pk_fma_f32 v[196:197], v[24:25], v[212:213], v[244:245]
	v_pk_fma_f32 v[138:139], v[18:19], v[154:155], v[238:239]
	v_pk_fma_f32 v[198:199], v[26:27], v[214:215], v[246:247]
	v_pk_fma_f32 v[140:141], v[20:21], v[156:157], v[240:241]
	v_pk_fma_f32 v[200:201], v[28:29], v[216:217], v[248:249]
	v_pk_fma_f32 v[142:143], v[22:23], v[158:159], v[242:243]
	v_pk_fma_f32 v[202:203], v[30:31], v[218:219], v[250:251]
	v_pk_fma_f32 v[136:137], v[32:33], v[160:161], v[136:137]
	v_pk_fma_f32 v[196:197], v[40:41], v[220:221], v[196:197]
	v_pk_fma_f32 v[138:139], v[34:35], v[162:163], v[138:139]
	v_pk_fma_f32 v[198:199], v[42:43], v[222:223], v[198:199]
	v_pk_fma_f32 v[140:141], v[36:37], v[164:165], v[140:141]
	v_pk_fma_f32 v[200:201], v[44:45], v[224:225], v[200:201]
	v_pk_fma_f32 v[142:143], v[38:39], v[166:167], v[142:143]
	v_pk_fma_f32 v[202:203], v[46:47], v[226:227], v[202:203]
	v_pk_fma_f32 v[136:137], v[48:49], v[168:169], v[136:137]
	v_pk_fma_f32 v[196:197], v[56:57], v[228:229], v[196:197]
	v_pk_fma_f32 v[138:139], v[50:51], v[170:171], v[138:139]
	v_pk_fma_f32 v[198:199], v[58:59], v[230:231], v[198:199]
	v_pk_fma_f32 v[140:141], v[52:53], v[172:173], v[140:141]
	v_pk_fma_f32 v[200:201], v[60:61], v[232:233], v[200:201]
	v_pk_fma_f32 v[142:143], v[54:55], v[174:175], v[142:143]
	v_pk_fma_f32 v[202:203], v[62:63], v[234:235], v[202:203]
	v_pk_mul_f32 v[184:185], v[136:137], v[180:181]
	v_pk_mul_f32 v[186:187], v[138:139], v[180:181]
	v_pk_mul_f32 v[188:189], v[140:141], v[180:181]
	v_pk_mul_f32 v[190:191], v[142:143], v[180:181]
	v_exp_f32_e32 v184, v184
	v_exp_f32_e32 v185, v185
	v_exp_f32_e32 v186, v186
	v_exp_f32_e32 v187, v187
	v_exp_f32_e32 v188, v188
	v_exp_f32_e32 v189, v189
	v_exp_f32_e32 v190, v190
	v_exp_f32_e32 v191, v191
	s_nop 0
	v_pk_add_f32 v[184:185], v[184:185], v[144:145]
	v_pk_add_f32 v[186:187], v[186:187], v[144:145]
	v_pk_add_f32 v[188:189], v[188:189], v[144:145]
	v_pk_add_f32 v[190:191], v[190:191], v[144:145]
	v_rcp_f32_e32 v184, v184
	v_rcp_f32_e32 v185, v185
	v_rcp_f32_e32 v186, v186
	v_rcp_f32_e32 v187, v187
	v_rcp_f32_e32 v188, v188
	v_rcp_f32_e32 v189, v189
	v_rcp_f32_e32 v190, v190
	v_rcp_f32_e32 v191, v191
	s_nop 0
	v_pk_mul_f32 v[136:137], v[136:137], v[184:185]
	v_pk_mul_f32 v[138:139], v[138:139], v[186:187]
	v_pk_mul_f32 v[140:141], v[140:141], v[188:189]
	v_pk_mul_f32 v[142:143], v[142:143], v[190:191]
	v_pk_mul_f32 v[136:137], v[136:137], v[196:197]
	v_pk_mul_f32 v[138:139], v[138:139], v[198:199]
	v_pk_mul_f32 v[140:141], v[140:141], v[200:201]
	v_pk_mul_f32 v[142:143], v[142:143], v[202:203]
	v_cvt_pk_bf16_f32 v12, v136, v137
	v_cvt_pk_bf16_f32 v13, v138, v139
	v_cvt_pk_bf16_f32 v14, v140, v141
	v_cvt_pk_bf16_f32 v15, v142, v143
	global_store_dwordx4 v6, v[12:15], s[36:37]
	v_add_u32_e32 v6, 5632, v6
	s_waitcnt vmcnt(23)
	v_lshlrev_b32_e32 v16, 16, v88
	v_and_b32_e32 v17, s99, v88
	v_lshlrev_b32_e32 v18, 16, v89
	v_and_b32_e32 v19, s99, v89
	v_lshlrev_b32_e32 v20, 16, v90
	v_and_b32_e32 v21, s99, v90
	v_lshlrev_b32_e32 v22, 16, v91
	v_and_b32_e32 v23, s99, v91
	v_lshlrev_b32_e32 v24, 16, v92
	v_and_b32_e32 v25, s99, v92
	v_lshlrev_b32_e32 v26, 16, v93
	v_and_b32_e32 v27, s99, v93
	v_lshlrev_b32_e32 v28, 16, v94
	v_and_b32_e32 v29, s99, v94
	v_lshlrev_b32_e32 v30, 16, v95
	v_and_b32_e32 v31, s99, v95
	v_add_u32_e32 v10, 143104, v5
	global_load_dwordx4 v[88:91], v10, s[2:3] offset:-2816
	global_load_dwordx4 v[92:95], v10, s[2:3] offset:2816
	v_pk_fma_f32 v[136:137], v[32:33], v[152:153], v[236:237]
	v_pk_fma_f32 v[196:197], v[40:41], v[212:213], v[244:245]
	v_pk_fma_f32 v[138:139], v[34:35], v[154:155], v[238:239]
	v_pk_fma_f32 v[198:199], v[42:43], v[214:215], v[246:247]
	v_pk_fma_f32 v[140:141], v[36:37], v[156:157], v[240:241]
	v_pk_fma_f32 v[200:201], v[44:45], v[216:217], v[248:249]
	v_pk_fma_f32 v[142:143], v[38:39], v[158:159], v[242:243]
	v_pk_fma_f32 v[202:203], v[46:47], v[218:219], v[250:251]
	v_pk_fma_f32 v[136:137], v[48:49], v[160:161], v[136:137]
	v_pk_fma_f32 v[196:197], v[56:57], v[220:221], v[196:197]
	v_pk_fma_f32 v[138:139], v[50:51], v[162:163], v[138:139]
	v_pk_fma_f32 v[198:199], v[58:59], v[222:223], v[198:199]
	v_pk_fma_f32 v[140:141], v[52:53], v[164:165], v[140:141]
	v_pk_fma_f32 v[200:201], v[60:61], v[224:225], v[200:201]
	v_pk_fma_f32 v[142:143], v[54:55], v[166:167], v[142:143]
	v_pk_fma_f32 v[202:203], v[62:63], v[226:227], v[202:203]
	v_pk_fma_f32 v[136:137], v[16:17], v[168:169], v[136:137]
	v_pk_fma_f32 v[196:197], v[24:25], v[228:229], v[196:197]
	v_pk_fma_f32 v[138:139], v[18:19], v[170:171], v[138:139]
	v_pk_fma_f32 v[198:199], v[26:27], v[230:231], v[198:199]
	v_pk_fma_f32 v[140:141], v[20:21], v[172:173], v[140:141]
	v_pk_fma_f32 v[200:201], v[28:29], v[232:233], v[200:201]
	v_pk_fma_f32 v[142:143], v[22:23], v[174:175], v[142:143]
	v_pk_fma_f32 v[202:203], v[30:31], v[234:235], v[202:203]
	v_pk_mul_f32 v[184:185], v[136:137], v[180:181]
	v_pk_mul_f32 v[186:187], v[138:139], v[180:181]
	v_pk_mul_f32 v[188:189], v[140:141], v[180:181]
	v_pk_mul_f32 v[190:191], v[142:143], v[180:181]
	v_exp_f32_e32 v184, v184
	v_exp_f32_e32 v185, v185
	v_exp_f32_e32 v186, v186
	v_exp_f32_e32 v187, v187
	v_exp_f32_e32 v188, v188
	v_exp_f32_e32 v189, v189
	v_exp_f32_e32 v190, v190
	v_exp_f32_e32 v191, v191
	s_nop 0
	v_pk_add_f32 v[184:185], v[184:185], v[144:145]
	v_pk_add_f32 v[186:187], v[186:187], v[144:145]
	v_pk_add_f32 v[188:189], v[188:189], v[144:145]
	v_pk_add_f32 v[190:191], v[190:191], v[144:145]
	v_rcp_f32_e32 v184, v184
	v_rcp_f32_e32 v185, v185
	v_rcp_f32_e32 v186, v186
	v_rcp_f32_e32 v187, v187
	v_rcp_f32_e32 v188, v188
	v_rcp_f32_e32 v189, v189
	v_rcp_f32_e32 v190, v190
	v_rcp_f32_e32 v191, v191
	s_nop 0
	v_pk_mul_f32 v[136:137], v[136:137], v[184:185]
	v_pk_mul_f32 v[138:139], v[138:139], v[186:187]
	v_pk_mul_f32 v[140:141], v[140:141], v[188:189]
	v_pk_mul_f32 v[142:143], v[142:143], v[190:191]
	v_pk_mul_f32 v[136:137], v[136:137], v[196:197]
	v_pk_mul_f32 v[138:139], v[138:139], v[198:199]
	v_pk_mul_f32 v[140:141], v[140:141], v[200:201]
	v_pk_mul_f32 v[142:143], v[142:143], v[202:203]
	v_cvt_pk_bf16_f32 v12, v136, v137
	v_cvt_pk_bf16_f32 v13, v138, v139
	v_cvt_pk_bf16_f32 v14, v140, v141
	v_cvt_pk_bf16_f32 v15, v142, v143
	global_store_dwordx4 v6, v[12:15], s[36:37]
	v_add_u32_e32 v6, 5632, v6
	s_waitcnt vmcnt(23)
; __device__ __forceinline__ unsigned cvt_pk_bf16(float lo, float hi) { unsigned r; asm volatile("v_cvt_pk_bf16_f32 %0, %1, %2" : "=v"(r) : "v"(lo), "v"(hi)); return r; }
; __device__ __forceinline__ float silu_f(float x) { return x * __builtin_amdgcn_rcpf(1.0f + __builtin_amdgcn_exp2f(-LOG2E * x)); }
; __device__ __forceinline__ float bflo(unsigned w) { return __uint_as_float(w << 16); }
; __device__ __forceinline__ float bfhi(unsigned w) { return __uint_as_float(w & 0xffff0000u); }
; __device__ __forceinline__ void conv_phase(const bf16_t* Z, bf16_t* UA, const float* cw, const float* cb, int nrows, int rowoff) {
;     ...
;         for (int rr = 0; rr < 16; ++rr) {
;             u32x4 na = zero, ng = zero; if (rr < 15 || has_right) { na = *(const u32x4*)(zp + (size_t)(rr + 1) * FFN2); ng = *(const u32x4*)(zp + (size_t)(rr + 1) * FFN2 + FFN); }
;             u32x4 o;
; #pragma unroll
;             for (int e2 = 0; e2 < 4; ++e2) {
;                 const float a0 = bflo(pa[e2]) * wa[0][2 * e2] + bflo(ca[e2]) * wa[1][2 * e2] + bflo(na[e2]) * wa[2][2 * e2] + ba[2 * e2];
;                 const float a1 = bfhi(pa[e2]) * wa[0][2 * e2 + 1] + bfhi(ca[e2]) * wa[1][2 * e2 + 1] + bfhi(na[e2]) * wa[2][2 * e2 + 1] + ba[2 * e2 + 1];
;                 const float g0 = bflo(pg[e2]) * wg[0][2 * e2] + bflo(cgv[e2]) * wg[1][2 * e2] + bflo(ng[e2]) * wg[2][2 * e2] + bg[2 * e2];
;                 const float g1 = bfhi(pg[e2]) * wg[0][2 * e2 + 1] + bfhi(cgv[e2]) * wg[1][2 * e2 + 1] + bfhi(ng[e2]) * wg[2][2 * e2 + 1] + bg[2 * e2 + 1];
;                 o[e2] = cvt_pk_bf16(silu_f(a0) * g0, silu_f(a1) * g1); }
;             *(u32x4*)(UA + (size_t)(r0 + rr) * FFN + c0) = o;
;             pa = ca; pg = cgv; ca = na; cgv = ng;
	v_lshlrev_b32_e32 v32, 16, v96
	v_and_b32_e32 v33, s99, v96
	v_lshlrev_b32_e32 v34, 16, v97
	v_and_b32_e32 v35, s99, v97
	v_lshlrev_b32_e32 v36, 16, v98
	v_and_b32_e32 v37, s99, v98
	v_lshlrev_b32_e32 v38, 16, v99
	v_and_b32_e32 v39, s99, v99
	v_lshlrev_b32_e32 v40, 16, v100
	v_and_b32_e32 v41, s99, v100
	v_lshlrev_b32_e32 v42, 16, v101
	v_and_b32_e32 v43, s99, v101
	v_lshlrev_b32_e32 v44, 16, v102
	v_and_b32_e32 v45, s99, v102
	v_lshlrev_b32_e32 v46, 16, v103
	v_and_b32_e32 v47, s99, v103
	v_add_u32_e32 v11, 154368, v5
	global_load_dwordx4 v[96:99], v11, s[2:3] offset:-2816
	global_load_dwordx4 v[100:103], v11, s[2:3] offset:2816
	v_pk_fma_f32 v[136:137], v[48:49], v[152:153], v[236:237]
	v_pk_fma_f32 v[196:197], v[56:57], v[212:213], v[244:245]
	v_pk_fma_f32 v[138:139], v[50:51], v[154:155], v[238:239]
	v_pk_fma_f32 v[198:199], v[58:59], v[214:215], v[246:247]
	v_pk_fma_f32 v[140:141], v[52:53], v[156:157], v[240:241]
	v_pk_fma_f32 v[200:201], v[60:61], v[216:217], v[248:249]
	v_pk_fma_f32 v[142:143], v[54:55], v[158:159], v[242:243]
	v_pk_fma_f32 v[202:203], v[62:63], v[218:219], v[250:251]
	v_pk_fma_f32 v[136:137], v[16:17], v[160:161], v[136:137]
	v_pk_fma_f32 v[196:197], v[24:25], v[220:221], v[196:197]
	v_pk_fma_f32 v[138:139], v[18:19], v[162:163], v[138:139]
	v_pk_fma_f32 v[198:199], v[26:27], v[222:223], v[198:199]
	v_pk_fma_f32 v[140:141], v[20:21], v[164:165], v[140:141]
	v_pk_fma_f32 v[200:201], v[28:29], v[224:225], v[200:201]
	v_pk_fma_f32 v[142:143], v[22:23], v[166:167], v[142:143]
	v_pk_fma_f32 v[202:203], v[30:31], v[226:227], v[202:203]
	v_pk_fma_f32 v[136:137], v[32:33], v[168:169], v[136:137]
	v_pk_fma_f32 v[196:197], v[40:41], v[228:229], v[196:197]
	v_pk_fma_f32 v[138:139], v[34:35], v[170:171], v[138:139]
	v_pk_fma_f32 v[198:199], v[42:43], v[230:231], v[198:199]
	v_pk_fma_f32 v[140:141], v[36:37], v[172:173], v[140:141]
	v_pk_fma_f32 v[200:201], v[44:45], v[232:233], v[200:201]
	v_pk_fma_f32 v[142:143], v[38:39], v[174:175], v[142:143]
	v_pk_fma_f32 v[202:203], v[46:47], v[234:235], v[202:203]
	v_pk_mul_f32 v[184:185], v[136:137], v[180:181]
	v_pk_mul_f32 v[186:187], v[138:139], v[180:181]
	v_pk_mul_f32 v[188:189], v[140:141], v[180:181]
	v_pk_mul_f32 v[190:191], v[142:143], v[180:181]
	v_exp_f32_e32 v184, v184
	v_exp_f32_e32 v185, v185
	v_exp_f32_e32 v186, v186
	v_exp_f32_e32 v187, v187
	v_exp_f32_e32 v188, v188
	v_exp_f32_e32 v189, v189
	v_exp_f32_e32 v190, v190
	v_exp_f32_e32 v191, v191
	s_nop 0
	v_pk_add_f32 v[184:185], v[184:185], v[144:145]
	v_pk_add_f32 v[186:187], v[186:187], v[144:145]
	v_pk_add_f32 v[188:189], v[188:189], v[144:145]
	v_pk_add_f32 v[190:191], v[190:191], v[144:145]
	v_rcp_f32_e32 v184, v184
	v_rcp_f32_e32 v185, v185
	v_rcp_f32_e32 v186, v186
	v_rcp_f32_e32 v187, v187
	v_rcp_f32_e32 v188, v188
	v_rcp_f32_e32 v189, v189
	v_rcp_f32_e32 v190, v190
	v_rcp_f32_e32 v191, v191
	s_nop 0
	v_pk_mul_f32 v[136:137], v[136:137], v[184:185]
	v_pk_mul_f32 v[138:139], v[138:139], v[186:187]
	v_pk_mul_f32 v[140:141], v[140:141], v[188:189]
	v_pk_mul_f32 v[142:143], v[142:143], v[190:191]
	v_pk_mul_f32 v[136:137], v[136:137], v[196:197]
	v_pk_mul_f32 v[138:139], v[138:139], v[198:199]
	v_pk_mul_f32 v[140:141], v[140:141], v[200:201]
	v_pk_mul_f32 v[142:143], v[142:143], v[202:203]
	v_cvt_pk_bf16_f32 v12, v136, v137
	v_cvt_pk_bf16_f32 v13, v138, v139
	v_cvt_pk_bf16_f32 v14, v140, v141
	v_cvt_pk_bf16_f32 v15, v142, v143
	global_store_dwordx4 v6, v[12:15], s[36:37]
	v_add_u32_e32 v6, 5632, v6
	s_waitcnt vmcnt(23)
	v_lshlrev_b32_e32 v48, 16, v104
	v_and_b32_e32 v49, s99, v104
	v_lshlrev_b32_e32 v50, 16, v105
	v_and_b32_e32 v51, s99, v105
	v_lshlrev_b32_e32 v52, 16, v106
	v_and_b32_e32 v53, s99, v106
	v_lshlrev_b32_e32 v54, 16, v107
	v_and_b32_e32 v55, s99, v107
	v_lshlrev_b32_e32 v56, 16, v108
	v_and_b32_e32 v57, s99, v108
	v_lshlrev_b32_e32 v58, 16, v109
	v_and_b32_e32 v59, s99, v109
	v_lshlrev_b32_e32 v60, 16, v110
	v_and_b32_e32 v61, s99, v110
	v_lshlrev_b32_e32 v62, 16, v111
	v_and_b32_e32 v63, s99, v111
	v_add_u32_e32 v10, 165632, v5
	global_load_dwordx4 v[104:107], v10, s[2:3] offset:-2816
	global_load_dwordx4 v[108:111], v10, s[2:3] offset:2816
	v_pk_fma_f32 v[136:137], v[16:17], v[152:153], v[236:237]
	v_pk_fma_f32 v[196:197], v[24:25], v[212:213], v[244:245]
	v_pk_fma_f32 v[138:139], v[18:19], v[154:155], v[238:239]
	v_pk_fma_f32 v[198:199], v[26:27], v[214:215], v[246:247]
	v_pk_fma_f32 v[140:141], v[20:21], v[156:157], v[240:241]
	v_pk_fma_f32 v[200:201], v[28:29], v[216:217], v[248:249]
	v_pk_fma_f32 v[142:143], v[22:23], v[158:159], v[242:243]
	v_pk_fma_f32 v[202:203], v[30:31], v[218:219], v[250:251]
	v_pk_fma_f32 v[136:137], v[32:33], v[160:161], v[136:137]
	v_pk_fma_f32 v[196:197], v[40:41], v[220:221], v[196:197]
	v_pk_fma_f32 v[138:139], v[34:35], v[162:163], v[138:139]
	v_pk_fma_f32 v[198:199], v[42:43], v[222:223], v[198:199]
	v_pk_fma_f32 v[140:141], v[36:37], v[164:165], v[140:141]
	v_pk_fma_f32 v[200:201], v[44:45], v[224:225], v[200:201]
	v_pk_fma_f32 v[142:143], v[38:39], v[166:167], v[142:143]
	v_pk_fma_f32 v[202:203], v[46:47], v[226:227], v[202:203]
	v_pk_fma_f32 v[136:137], v[48:49], v[168:169], v[136:137]
	v_pk_fma_f32 v[196:197], v[56:57], v[228:229], v[196:197]
	v_pk_fma_f32 v[138:139], v[50:51], v[170:171], v[138:139]
	v_pk_fma_f32 v[198:199], v[58:59], v[230:231], v[198:199]
	v_pk_fma_f32 v[140:141], v[52:53], v[172:173], v[140:141]
	v_pk_fma_f32 v[200:201], v[60:61], v[232:233], v[200:201]
	v_pk_fma_f32 v[142:143], v[54:55], v[174:175], v[142:143]
	v_pk_fma_f32 v[202:203], v[62:63], v[234:235], v[202:203]
	v_pk_mul_f32 v[184:185], v[136:137], v[180:181]
	v_pk_mul_f32 v[186:187], v[138:139], v[180:181]
	v_pk_mul_f32 v[188:189], v[140:141], v[180:181]
	v_pk_mul_f32 v[190:191], v[142:143], v[180:181]
	v_exp_f32_e32 v184, v184
	v_exp_f32_e32 v185, v185
	v_exp_f32_e32 v186, v186
	v_exp_f32_e32 v187, v187
	v_exp_f32_e32 v188, v188
	v_exp_f32_e32 v189, v189
	v_exp_f32_e32 v190, v190
	v_exp_f32_e32 v191, v191
	s_nop 0
	v_pk_add_f32 v[184:185], v[184:185], v[144:145]
	v_pk_add_f32 v[186:187], v[186:187], v[144:145]
	v_pk_add_f32 v[188:189], v[188:189], v[144:145]
	v_pk_add_f32 v[190:191], v[190:191], v[144:145]
	v_rcp_f32_e32 v184, v184
	v_rcp_f32_e32 v185, v185
	v_rcp_f32_e32 v186, v186
	v_rcp_f32_e32 v187, v187
	v_rcp_f32_e32 v188, v188
	v_rcp_f32_e32 v189, v189
	v_rcp_f32_e32 v190, v190
	v_rcp_f32_e32 v191, v191
	s_nop 0
	v_pk_mul_f32 v[136:137], v[136:137], v[184:185]
	v_pk_mul_f32 v[138:139], v[138:139], v[186:187]
	v_pk_mul_f32 v[140:141], v[140:141], v[188:189]
	v_pk_mul_f32 v[142:143], v[142:143], v[190:191]
	v_pk_mul_f32 v[136:137], v[136:137], v[196:197]
	v_pk_mul_f32 v[138:139], v[138:139], v[198:199]
	v_pk_mul_f32 v[140:141], v[140:141], v[200:201]
	v_pk_mul_f32 v[142:143], v[142:143], v[202:203]
	v_cvt_pk_bf16_f32 v12, v136, v137
	v_cvt_pk_bf16_f32 v13, v138, v139
	v_cvt_pk_bf16_f32 v14, v140, v141
	v_cvt_pk_bf16_f32 v15, v142, v143
	global_store_dwordx4 v6, v[12:15], s[36:37]
	v_add_u32_e32 v6, 5632, v6
	s_waitcnt vmcnt(23)
; __device__ __forceinline__ unsigned cvt_pk_bf16(float lo, float hi) { unsigned r; asm volatile("v_cvt_pk_bf16_f32 %0, %1, %2" : "=v"(r) : "v"(lo), "v"(hi)); return r; }
; __device__ __forceinline__ float silu_f(float x) { return x * __builtin_amdgcn_rcpf(1.0f + __builtin_amdgcn_exp2f(-LOG2E * x)); }
; __device__ __forceinline__ float bflo(unsigned w) { return __uint_as_float(w << 16); }
; __device__ __forceinline__ float bfhi(unsigned w) { return __uint_as_float(w & 0xffff0000u); }
; __device__ __forceinline__ void conv_phase(const bf16_t* Z, bf16_t* UA, const float* cw, const float* cb, int nrows, int rowoff) {
;     ...
;         for (int rr = 0; rr < 16; ++rr) {
;             u32x4 na = zero, ng = zero; if (rr < 15 || has_right) { na = *(const u32x4*)(zp + (size_t)(rr + 1) * FFN2); ng = *(const u32x4*)(zp + (size_t)(rr + 1) * FFN2 + FFN); }
;             u32x4 o;
; #pragma unroll
;             for (int e2 = 0; e2 < 4; ++e2) {
;                 const float a0 = bflo(pa[e2]) * wa[0][2 * e2] + bflo(ca[e2]) * wa[1][2 * e2] + bflo(na[e2]) * wa[2][2 * e2] + ba[2 * e2];
;                 const float a1 = bfhi(pa[e2]) * wa[0][2 * e2 + 1] + bfhi(ca[e2]) * wa[1][2 * e2 + 1] + bfhi(na[e2]) * wa[2][2 * e2 + 1] + ba[2 * e2 + 1];
;                 const float g0 = bflo(pg[e2]) * wg[0][2 * e2] + bflo(cgv[e2]) * wg[1][2 * e2] + bflo(ng[e2]) * wg[2][2 * e2] + bg[2 * e2];
;                 const float g1 = bfhi(pg[e2]) * wg[0][2 * e2 + 1] + bfhi(cgv[e2]) * wg[1][2 * e2 + 1] + bfhi(ng[e2]) * wg[2][2 * e2 + 1] + bg[2 * e2 + 1];
;                 o[e2] = cvt_pk_bf16(silu_f(a0) * g0, silu_f(a1) * g1); }
;             *(u32x4*)(UA + (size_t)(r0 + rr) * FFN + c0) = o;
;             pa = ca; pg = cgv; ca = na; cgv = ng;
	v_lshlrev_b32_e32 v16, 16, v112
	v_and_b32_e32 v17, s99, v112
	v_lshlrev_b32_e32 v18, 16, v113
	v_and_b32_e32 v19, s99, v113
	v_lshlrev_b32_e32 v20, 16, v114
	v_and_b32_e32 v21, s99, v114
	v_lshlrev_b32_e32 v22, 16, v115
	v_and_b32_e32 v23, s99, v115
	v_lshlrev_b32_e32 v24, 16, v116
	v_and_b32_e32 v25, s99, v116
	v_lshlrev_b32_e32 v26, 16, v117
	v_and_b32_e32 v27, s99, v117
	v_lshlrev_b32_e32 v28, 16, v118
	v_and_b32_e32 v29, s99, v118
	v_lshlrev_b32_e32 v30, 16, v119
	v_and_b32_e32 v31, s99, v119
	v_add_u32_e32 v11, 176896, v5
	global_load_dwordx4 v[112:115], v11, s[2:3] offset:-2816
	global_load_dwordx4 v[116:119], v11, s[2:3] offset:2816
	v_pk_fma_f32 v[136:137], v[32:33], v[152:153], v[236:237]
	v_pk_fma_f32 v[196:197], v[40:41], v[212:213], v[244:245]
	v_pk_fma_f32 v[138:139], v[34:35], v[154:155], v[238:239]
	v_pk_fma_f32 v[198:199], v[42:43], v[214:215], v[246:247]
	v_pk_fma_f32 v[140:141], v[36:37], v[156:157], v[240:241]
	v_pk_fma_f32 v[200:201], v[44:45], v[216:217], v[248:249]
	v_pk_fma_f32 v[142:143], v[38:39], v[158:159], v[242:243]
	v_pk_fma_f32 v[202:203], v[46:47], v[218:219], v[250:251]
	v_pk_fma_f32 v[136:137], v[48:49], v[160:161], v[136:137]
	v_pk_fma_f32 v[196:197], v[56:57], v[220:221], v[196:197]
	v_pk_fma_f32 v[138:139], v[50:51], v[162:163], v[138:139]
	v_pk_fma_f32 v[198:199], v[58:59], v[222:223], v[198:199]
	v_pk_fma_f32 v[140:141], v[52:53], v[164:165], v[140:141]
	v_pk_fma_f32 v[200:201], v[60:61], v[224:225], v[200:201]
	v_pk_fma_f32 v[142:143], v[54:55], v[166:167], v[142:143]
	v_pk_fma_f32 v[202:203], v[62:63], v[226:227], v[202:203]
	v_pk_fma_f32 v[136:137], v[16:17], v[168:169], v[136:137]
	v_pk_fma_f32 v[196:197], v[24:25], v[228:229], v[196:197]
	v_pk_fma_f32 v[138:139], v[18:19], v[170:171], v[138:139]
	v_pk_fma_f32 v[198:199], v[26:27], v[230:231], v[198:199]
	v_pk_fma_f32 v[140:141], v[20:21], v[172:173], v[140:141]
	v_pk_fma_f32 v[200:201], v[28:29], v[232:233], v[200:201]
	v_pk_fma_f32 v[142:143], v[22:23], v[174:175], v[142:143]
	v_pk_fma_f32 v[202:203], v[30:31], v[234:235], v[202:203]
	v_pk_mul_f32 v[184:185], v[136:137], v[180:181]
	v_pk_mul_f32 v[186:187], v[138:139], v[180:181]
	v_pk_mul_f32 v[188:189], v[140:141], v[180:181]
	v_pk_mul_f32 v[190:191], v[142:143], v[180:181]
	v_exp_f32_e32 v184, v184
	v_exp_f32_e32 v185, v185
	v_exp_f32_e32 v186, v186
	v_exp_f32_e32 v187, v187
	v_exp_f32_e32 v188, v188
	v_exp_f32_e32 v189, v189
	v_exp_f32_e32 v190, v190
	v_exp_f32_e32 v191, v191
	s_nop 0
	v_pk_add_f32 v[184:185], v[184:185], v[144:145]
	v_pk_add_f32 v[186:187], v[186:187], v[144:145]
	v_pk_add_f32 v[188:189], v[188:189], v[144:145]
	v_pk_add_f32 v[190:191], v[190:191], v[144:145]
	v_rcp_f32_e32 v184, v184
	v_rcp_f32_e32 v185, v185
	v_rcp_f32_e32 v186, v186
	v_rcp_f32_e32 v187, v187
	v_rcp_f32_e32 v188, v188
	v_rcp_f32_e32 v189, v189
	v_rcp_f32_e32 v190, v190
	v_rcp_f32_e32 v191, v191
	s_nop 0
	v_pk_mul_f32 v[136:137], v[136:137], v[184:185]
	v_pk_mul_f32 v[138:139], v[138:139], v[186:187]
	v_pk_mul_f32 v[140:141], v[140:141], v[188:189]
	v_pk_mul_f32 v[142:143], v[142:143], v[190:191]
	v_pk_mul_f32 v[136:137], v[136:137], v[196:197]
	v_pk_mul_f32 v[138:139], v[138:139], v[198:199]
	v_pk_mul_f32 v[140:141], v[140:141], v[200:201]
	v_pk_mul_f32 v[142:143], v[142:143], v[202:203]
	v_cvt_pk_bf16_f32 v12, v136, v137
	v_cvt_pk_bf16_f32 v13, v138, v139
	v_cvt_pk_bf16_f32 v14, v140, v141
	v_cvt_pk_bf16_f32 v15, v142, v143
	global_store_dwordx4 v6, v[12:15], s[36:37]
	v_add_u32_e32 v6, 5632, v6
	s_waitcnt vmcnt(23)
	v_lshlrev_b32_e32 v32, 16, v120
	v_and_b32_e32 v33, s99, v120
	v_lshlrev_b32_e32 v34, 16, v121
	v_and_b32_e32 v35, s99, v121
	v_lshlrev_b32_e32 v36, 16, v122
	v_and_b32_e32 v37, s99, v122
	v_lshlrev_b32_e32 v38, 16, v123
	v_and_b32_e32 v39, s99, v123
	v_lshlrev_b32_e32 v40, 16, v124
	v_and_b32_e32 v41, s99, v124
	v_lshlrev_b32_e32 v42, 16, v125
	v_and_b32_e32 v43, s99, v125
	v_lshlrev_b32_e32 v44, 16, v126
	v_and_b32_e32 v45, s99, v126
	v_lshlrev_b32_e32 v46, 16, v127
	v_and_b32_e32 v47, s99, v127
	v_add_u32_e32 v10, 188160, v5
	global_load_dwordx4 v[120:123], v10, s[2:3] offset:-2816
	global_load_dwordx4 v[124:127], v10, s[2:3] offset:2816
	v_pk_fma_f32 v[136:137], v[48:49], v[152:153], v[236:237]
	v_pk_fma_f32 v[196:197], v[56:57], v[212:213], v[244:245]
	v_pk_fma_f32 v[138:139], v[50:51], v[154:155], v[238:239]
	v_pk_fma_f32 v[198:199], v[58:59], v[214:215], v[246:247]
	v_pk_fma_f32 v[140:141], v[52:53], v[156:157], v[240:241]
	v_pk_fma_f32 v[200:201], v[60:61], v[216:217], v[248:249]
	v_pk_fma_f32 v[142:143], v[54:55], v[158:159], v[242:243]
	v_pk_fma_f32 v[202:203], v[62:63], v[218:219], v[250:251]
	v_pk_fma_f32 v[136:137], v[16:17], v[160:161], v[136:137]
	v_pk_fma_f32 v[196:197], v[24:25], v[220:221], v[196:197]
	v_pk_fma_f32 v[138:139], v[18:19], v[162:163], v[138:139]
	v_pk_fma_f32 v[198:199], v[26:27], v[222:223], v[198:199]
	v_pk_fma_f32 v[140:141], v[20:21], v[164:165], v[140:141]
	v_pk_fma_f32 v[200:201], v[28:29], v[224:225], v[200:201]
	v_pk_fma_f32 v[142:143], v[22:23], v[166:167], v[142:143]
	v_pk_fma_f32 v[202:203], v[30:31], v[226:227], v[202:203]
	v_pk_fma_f32 v[136:137], v[32:33], v[168:169], v[136:137]
	v_pk_fma_f32 v[196:197], v[40:41], v[228:229], v[196:197]
	v_pk_fma_f32 v[138:139], v[34:35], v[170:171], v[138:139]
	v_pk_fma_f32 v[198:199], v[42:43], v[230:231], v[198:199]
	v_pk_fma_f32 v[140:141], v[36:37], v[172:173], v[140:141]
	v_pk_fma_f32 v[200:201], v[44:45], v[232:233], v[200:201]
	v_pk_fma_f32 v[142:143], v[38:39], v[174:175], v[142:143]
	v_pk_fma_f32 v[202:203], v[46:47], v[234:235], v[202:203]
	v_pk_mul_f32 v[184:185], v[136:137], v[180:181]
	v_pk_mul_f32 v[186:187], v[138:139], v[180:181]
	v_pk_mul_f32 v[188:189], v[140:141], v[180:181]
	v_pk_mul_f32 v[190:191], v[142:143], v[180:181]
	v_exp_f32_e32 v184, v184
	v_exp_f32_e32 v185, v185
	v_exp_f32_e32 v186, v186
	v_exp_f32_e32 v187, v187
	v_exp_f32_e32 v188, v188
	v_exp_f32_e32 v189, v189
	v_exp_f32_e32 v190, v190
	v_exp_f32_e32 v191, v191
	s_nop 0
	v_pk_add_f32 v[184:185], v[184:185], v[144:145]
	v_pk_add_f32 v[186:187], v[186:187], v[144:145]
	v_pk_add_f32 v[188:189], v[188:189], v[144:145]
	v_pk_add_f32 v[190:191], v[190:191], v[144:145]
	v_rcp_f32_e32 v184, v184
	v_rcp_f32_e32 v185, v185
	v_rcp_f32_e32 v186, v186
	v_rcp_f32_e32 v187, v187
	v_rcp_f32_e32 v188, v188
	v_rcp_f32_e32 v189, v189
	v_rcp_f32_e32 v190, v190
	v_rcp_f32_e32 v191, v191
	s_nop 0
	v_pk_mul_f32 v[136:137], v[136:137], v[184:185]
	v_pk_mul_f32 v[138:139], v[138:139], v[186:187]
	v_pk_mul_f32 v[140:141], v[140:141], v[188:189]
	v_pk_mul_f32 v[142:143], v[142:143], v[190:191]
	v_pk_mul_f32 v[136:137], v[136:137], v[196:197]
	v_pk_mul_f32 v[138:139], v[138:139], v[198:199]
	v_pk_mul_f32 v[140:141], v[140:141], v[200:201]
	v_pk_mul_f32 v[142:143], v[142:143], v[202:203]
	v_cvt_pk_bf16_f32 v12, v136, v137
	v_cvt_pk_bf16_f32 v13, v138, v139
	v_cvt_pk_bf16_f32 v14, v140, v141
	v_cvt_pk_bf16_f32 v15, v142, v143
	global_store_dwordx4 v6, v[12:15], s[36:37]
	v_add_u32_e32 v6, 5632, v6
	s_waitcnt vmcnt(23)
; __device__ __forceinline__ unsigned cvt_pk_bf16(float lo, float hi) { unsigned r; asm volatile("v_cvt_pk_bf16_f32 %0, %1, %2" : "=v"(r) : "v"(lo), "v"(hi)); return r; }
; __device__ __forceinline__ float silu_f(float x) { return x * __builtin_amdgcn_rcpf(1.0f + __builtin_amdgcn_exp2f(-LOG2E * x)); }
; __device__ __forceinline__ float bflo(unsigned w) { return __uint_as_float(w << 16); }
; __device__ __forceinline__ float bfhi(unsigned w) { return __uint_as_float(w & 0xffff0000u); }
; __device__ __forceinline__ void conv_phase(const bf16_t* Z, bf16_t* UA, const float* cw, const float* cb, int nrows, int rowoff) {
;     ...
;         for (int rr = 0; rr < 16; ++rr) {
;             u32x4 na = zero, ng = zero; if (rr < 15 || has_right) { na = *(const u32x4*)(zp + (size_t)(rr + 1) * FFN2); ng = *(const u32x4*)(zp + (size_t)(rr + 1) * FFN2 + FFN); }
;             u32x4 o;
; #pragma unroll
;             for (int e2 = 0; e2 < 4; ++e2) {
;                 const float a0 = bflo(pa[e2]) * wa[0][2 * e2] + bflo(ca[e2]) * wa[1][2 * e2] + bflo(na[e2]) * wa[2][2 * e2] + ba[2 * e2];
;                 const float a1 = bfhi(pa[e2]) * wa[0][2 * e2 + 1] + bfhi(ca[e2]) * wa[1][2 * e2 + 1] + bfhi(na[e2]) * wa[2][2 * e2 + 1] + ba[2 * e2 + 1];
;                 const float g0 = bflo(pg[e2]) * wg[0][2 * e2] + bflo(cgv[e2]) * wg[1][2 * e2] + bflo(ng[e2]) * wg[2][2 * e2] + bg[2 * e2];
;                 const float g1 = bfhi(pg[e2]) * wg[0][2 * e2 + 1] + bfhi(cgv[e2]) * wg[1][2 * e2 + 1] + bfhi(ng[e2]) * wg[2][2 * e2 + 1] + bg[2 * e2 + 1];
;                 o[e2] = cvt_pk_bf16(silu_f(a0) * g0, silu_f(a1) * g1); }
;             *(u32x4*)(UA + (size_t)(r0 + rr) * FFN + c0) = o;
;             pa = ca; pg = cgv; ca = na; cgv = ng;
	v_lshlrev_b32_e32 v48, 16, v128
	v_and_b32_e32 v49, s99, v128
	v_lshlrev_b32_e32 v50, 16, v129
	v_and_b32_e32 v51, s99, v129
	v_lshlrev_b32_e32 v52, 16, v130
	v_and_b32_e32 v53, s99, v130
	v_lshlrev_b32_e32 v54, 16, v131
	v_and_b32_e32 v55, s99, v131
	v_lshlrev_b32_e32 v56, 16, v132
	v_and_b32_e32 v57, s99, v132
	v_lshlrev_b32_e32 v58, 16, v133
	v_and_b32_e32 v59, s99, v133
	v_lshlrev_b32_e32 v60, 16, v134
	v_and_b32_e32 v61, s99, v134
	v_lshlrev_b32_e32 v62, 16, v135
	v_and_b32_e32 v63, s99, v135
	v_add_u32_e32 v11, 199424, v5
	global_load_dwordx4 v[128:131], v11, s[2:3] offset:-2816
	global_load_dwordx4 v[132:135], v11, s[2:3] offset:2816
	v_pk_fma_f32 v[136:137], v[16:17], v[152:153], v[236:237]
	v_pk_fma_f32 v[196:197], v[24:25], v[212:213], v[244:245]
	v_pk_fma_f32 v[138:139], v[18:19], v[154:155], v[238:239]
	v_pk_fma_f32 v[198:199], v[26:27], v[214:215], v[246:247]
	v_pk_fma_f32 v[140:141], v[20:21], v[156:157], v[240:241]
	v_pk_fma_f32 v[200:201], v[28:29], v[216:217], v[248:249]
	v_pk_fma_f32 v[142:143], v[22:23], v[158:159], v[242:243]
	v_pk_fma_f32 v[202:203], v[30:31], v[218:219], v[250:251]
	v_pk_fma_f32 v[136:137], v[32:33], v[160:161], v[136:137]
	v_pk_fma_f32 v[196:197], v[40:41], v[220:221], v[196:197]
	v_pk_fma_f32 v[138:139], v[34:35], v[162:163], v[138:139]
	v_pk_fma_f32 v[198:199], v[42:43], v[222:223], v[198:199]
	v_pk_fma_f32 v[140:141], v[36:37], v[164:165], v[140:141]
	v_pk_fma_f32 v[200:201], v[44:45], v[224:225], v[200:201]
	v_pk_fma_f32 v[142:143], v[38:39], v[166:167], v[142:143]
	v_pk_fma_f32 v[202:203], v[46:47], v[226:227], v[202:203]
	v_pk_fma_f32 v[136:137], v[48:49], v[168:169], v[136:137]
	v_pk_fma_f32 v[196:197], v[56:57], v[228:229], v[196:197]
	v_pk_fma_f32 v[138:139], v[50:51], v[170:171], v[138:139]
	v_pk_fma_f32 v[198:199], v[58:59], v[230:231], v[198:199]
	v_pk_fma_f32 v[140:141], v[52:53], v[172:173], v[140:141]
	v_pk_fma_f32 v[200:201], v[60:61], v[232:233], v[200:201]
	v_pk_fma_f32 v[142:143], v[54:55], v[174:175], v[142:143]
	v_pk_fma_f32 v[202:203], v[62:63], v[234:235], v[202:203]
	v_pk_mul_f32 v[184:185], v[136:137], v[180:181]
	v_pk_mul_f32 v[186:187], v[138:139], v[180:181]
	v_pk_mul_f32 v[188:189], v[140:141], v[180:181]
	v_pk_mul_f32 v[190:191], v[142:143], v[180:181]
	v_exp_f32_e32 v184, v184
	v_exp_f32_e32 v185, v185
	v_exp_f32_e32 v186, v186
	v_exp_f32_e32 v187, v187
	v_exp_f32_e32 v188, v188
	v_exp_f32_e32 v189, v189
	v_exp_f32_e32 v190, v190
	v_exp_f32_e32 v191, v191
	s_nop 0
	v_pk_add_f32 v[184:185], v[184:185], v[144:145]
	v_pk_add_f32 v[186:187], v[186:187], v[144:145]
	v_pk_add_f32 v[188:189], v[188:189], v[144:145]
	v_pk_add_f32 v[190:191], v[190:191], v[144:145]
	v_rcp_f32_e32 v184, v184
	v_rcp_f32_e32 v185, v185
	v_rcp_f32_e32 v186, v186
	v_rcp_f32_e32 v187, v187
	v_rcp_f32_e32 v188, v188
	v_rcp_f32_e32 v189, v189
	v_rcp_f32_e32 v190, v190
	v_rcp_f32_e32 v191, v191
	s_nop 0
	v_pk_mul_f32 v[136:137], v[136:137], v[184:185]
	v_pk_mul_f32 v[138:139], v[138:139], v[186:187]
	v_pk_mul_f32 v[140:141], v[140:141], v[188:189]
	v_pk_mul_f32 v[142:143], v[142:143], v[190:191]
	v_pk_mul_f32 v[136:137], v[136:137], v[196:197]
	v_pk_mul_f32 v[138:139], v[138:139], v[198:199]
	v_pk_mul_f32 v[140:141], v[140:141], v[200:201]
	v_pk_mul_f32 v[142:143], v[142:143], v[202:203]
	v_cvt_pk_bf16_f32 v12, v136, v137
	v_cvt_pk_bf16_f32 v13, v138, v139
	v_cvt_pk_bf16_f32 v14, v140, v141
	v_cvt_pk_bf16_f32 v15, v142, v143
	global_store_dwordx4 v6, v[12:15], s[36:37]
	v_add_u32_e32 v6, 5632, v6
	s_waitcnt vmcnt(23)
	v_lshlrev_b32_e32 v16, 16, v64
	v_and_b32_e32 v17, s99, v64
	v_lshlrev_b32_e32 v18, 16, v65
	v_and_b32_e32 v19, s99, v65
	v_lshlrev_b32_e32 v20, 16, v66
	v_and_b32_e32 v21, s99, v66
	v_lshlrev_b32_e32 v22, 16, v67
	v_and_b32_e32 v23, s99, v67
	v_lshlrev_b32_e32 v24, 16, v68
	v_and_b32_e32 v25, s99, v68
	v_lshlrev_b32_e32 v26, 16, v69
	v_and_b32_e32 v27, s99, v69
	v_lshlrev_b32_e32 v28, 16, v70
	v_and_b32_e32 v29, s99, v70
	v_lshlrev_b32_e32 v30, 16, v71
	v_and_b32_e32 v31, s99, v71
	v_add_u32_e32 v10, 67051264, v5
	global_load_dwordx4 v[64:67], v10, s[2:3] offset:-2816
	global_load_dwordx4 v[68:71], v10, s[2:3] offset:2816
	v_pk_fma_f32 v[136:137], v[32:33], v[152:153], v[236:237]
	v_pk_fma_f32 v[196:197], v[40:41], v[212:213], v[244:245]
	v_pk_fma_f32 v[138:139], v[34:35], v[154:155], v[238:239]
	v_pk_fma_f32 v[198:199], v[42:43], v[214:215], v[246:247]
	v_pk_fma_f32 v[140:141], v[36:37], v[156:157], v[240:241]
	v_pk_fma_f32 v[200:201], v[44:45], v[216:217], v[248:249]
	v_pk_fma_f32 v[142:143], v[38:39], v[158:159], v[242:243]
	v_pk_fma_f32 v[202:203], v[46:47], v[218:219], v[250:251]
	v_pk_fma_f32 v[136:137], v[48:49], v[160:161], v[136:137]
	v_pk_fma_f32 v[196:197], v[56:57], v[220:221], v[196:197]
	v_pk_fma_f32 v[138:139], v[50:51], v[162:163], v[138:139]
	v_pk_fma_f32 v[198:199], v[58:59], v[222:223], v[198:199]
	v_pk_fma_f32 v[140:141], v[52:53], v[164:165], v[140:141]
	v_pk_fma_f32 v[200:201], v[60:61], v[224:225], v[200:201]
	v_pk_fma_f32 v[142:143], v[54:55], v[166:167], v[142:143]
	v_pk_fma_f32 v[202:203], v[62:63], v[226:227], v[202:203]
	v_pk_fma_f32 v[136:137], v[16:17], v[168:169], v[136:137]
	v_pk_fma_f32 v[196:197], v[24:25], v[228:229], v[196:197]
	v_pk_fma_f32 v[138:139], v[18:19], v[170:171], v[138:139]
	v_pk_fma_f32 v[198:199], v[26:27], v[230:231], v[198:199]
	v_pk_fma_f32 v[140:141], v[20:21], v[172:173], v[140:141]
	v_pk_fma_f32 v[200:201], v[28:29], v[232:233], v[200:201]
	v_pk_fma_f32 v[142:143], v[22:23], v[174:175], v[142:143]
	v_pk_fma_f32 v[202:203], v[30:31], v[234:235], v[202:203]
	v_pk_mul_f32 v[184:185], v[136:137], v[180:181]
	v_pk_mul_f32 v[186:187], v[138:139], v[180:181]
	v_pk_mul_f32 v[188:189], v[140:141], v[180:181]
	v_pk_mul_f32 v[190:191], v[142:143], v[180:181]
	v_exp_f32_e32 v184, v184
	v_exp_f32_e32 v185, v185
	v_exp_f32_e32 v186, v186
	v_exp_f32_e32 v187, v187
	v_exp_f32_e32 v188, v188
	v_exp_f32_e32 v189, v189
	v_exp_f32_e32 v190, v190
	v_exp_f32_e32 v191, v191
	s_nop 0
	v_pk_add_f32 v[184:185], v[184:185], v[144:145]
	v_pk_add_f32 v[186:187], v[186:187], v[144:145]
	v_pk_add_f32 v[188:189], v[188:189], v[144:145]
	v_pk_add_f32 v[190:191], v[190:191], v[144:145]
	v_rcp_f32_e32 v184, v184
	v_rcp_f32_e32 v185, v185
	v_rcp_f32_e32 v186, v186
	v_rcp_f32_e32 v187, v187
	v_rcp_f32_e32 v188, v188
	v_rcp_f32_e32 v189, v189
	v_rcp_f32_e32 v190, v190
	v_rcp_f32_e32 v191, v191
	s_nop 0
	v_pk_mul_f32 v[136:137], v[136:137], v[184:185]
	v_pk_mul_f32 v[138:139], v[138:139], v[186:187]
	v_pk_mul_f32 v[140:141], v[140:141], v[188:189]
	v_pk_mul_f32 v[142:143], v[142:143], v[190:191]
	v_pk_mul_f32 v[136:137], v[136:137], v[196:197]
	v_pk_mul_f32 v[138:139], v[138:139], v[198:199]
	v_pk_mul_f32 v[140:141], v[140:141], v[200:201]
	v_pk_mul_f32 v[142:143], v[142:143], v[202:203]
	v_cvt_pk_bf16_f32 v12, v136, v137
	v_cvt_pk_bf16_f32 v13, v138, v139
	v_cvt_pk_bf16_f32 v14, v140, v141
	v_cvt_pk_bf16_f32 v15, v142, v143
	global_store_dwordx4 v6, v[12:15], s[36:37]
	v_add_u32_e32 v6, 5632, v6
	s_waitcnt vmcnt(24)
; __device__ __forceinline__ unsigned cvt_pk_bf16(float lo, float hi) { unsigned r; asm volatile("v_cvt_pk_bf16_f32 %0, %1, %2" : "=v"(r) : "v"(lo), "v"(hi)); return r; }
; __device__ __forceinline__ float silu_f(float x) { return x * __builtin_amdgcn_rcpf(1.0f + __builtin_amdgcn_exp2f(-LOG2E * x)); }
; __device__ __forceinline__ float bflo(unsigned w) { return __uint_as_float(w << 16); }
; __device__ __forceinline__ float bfhi(unsigned w) { return __uint_as_float(w & 0xffff0000u); }
; __device__ __forceinline__ void conv_phase(const bf16_t* Z, bf16_t* UA, const float* cw, const float* cb, int nrows, int rowoff) {
;     ...
;         for (int rr = 0; rr < 16; ++rr) {
;             u32x4 na = zero, ng = zero; if (rr < 15 || has_right) { na = *(const u32x4*)(zp + (size_t)(rr + 1) * FFN2); ng = *(const u32x4*)(zp + (size_t)(rr + 1) * FFN2 + FFN); }
;             u32x4 o;
; #pragma unroll
;             for (int e2 = 0; e2 < 4; ++e2) {
;                 const float a0 = bflo(pa[e2]) * wa[0][2 * e2] + bflo(ca[e2]) * wa[1][2 * e2] + bflo(na[e2]) * wa[2][2 * e2] + ba[2 * e2];
;                 const float a1 = bfhi(pa[e2]) * wa[0][2 * e2 + 1] + bfhi(ca[e2]) * wa[1][2 * e2 + 1] + bfhi(na[e2]) * wa[2][2 * e2 + 1] + ba[2 * e2 + 1];
;                 const float g0 = bflo(pg[e2]) * wg[0][2 * e2] + bflo(cgv[e2]) * wg[1][2 * e2] + bflo(ng[e2]) * wg[2][2 * e2] + bg[2 * e2];
;                 const float g1 = bfhi(pg[e2]) * wg[0][2 * e2 + 1] + bfhi(cgv[e2]) * wg[1][2 * e2 + 1] + bfhi(ng[e2]) * wg[2][2 * e2 + 1] + bg[2 * e2 + 1];
;                 o[e2] = cvt_pk_bf16(silu_f(a0) * g0, silu_f(a1) * g1); }
;             *(u32x4*)(UA + (size_t)(r0 + rr) * FFN + c0) = o;
;             pa = ca; pg = cgv; ca = na; cgv = ng;
	v_lshlrev_b32_e32 v32, 16, v72
	v_and_b32_e32 v33, s99, v72
	v_lshlrev_b32_e32 v34, 16, v73
	v_and_b32_e32 v35, s99, v73
	v_lshlrev_b32_e32 v36, 16, v74
	v_and_b32_e32 v37, s99, v74
	v_lshlrev_b32_e32 v38, 16, v75
	v_and_b32_e32 v39, s99, v75
	v_lshlrev_b32_e32 v40, 16, v76
	v_and_b32_e32 v41, s99, v76
	v_lshlrev_b32_e32 v42, 16, v77
	v_and_b32_e32 v43, s99, v77
	v_lshlrev_b32_e32 v44, 16, v78
	v_and_b32_e32 v45, s99, v78
	v_lshlrev_b32_e32 v46, 16, v79
	v_and_b32_e32 v47, s99, v79
	v_add_u32_e32 v11, 67062528, v5
	global_load_dwordx4 v[72:75], v11, s[2:3] offset:-2816
	global_load_dwordx4 v[76:79], v11, s[2:3] offset:2816
	v_pk_fma_f32 v[136:137], v[48:49], v[152:153], v[236:237]
	v_pk_fma_f32 v[196:197], v[56:57], v[212:213], v[244:245]
	v_pk_fma_f32 v[138:139], v[50:51], v[154:155], v[238:239]
	v_pk_fma_f32 v[198:199], v[58:59], v[214:215], v[246:247]
	v_pk_fma_f32 v[140:141], v[52:53], v[156:157], v[240:241]
	v_pk_fma_f32 v[200:201], v[60:61], v[216:217], v[248:249]
	v_pk_fma_f32 v[142:143], v[54:55], v[158:159], v[242:243]
	v_pk_fma_f32 v[202:203], v[62:63], v[218:219], v[250:251]
	v_pk_fma_f32 v[136:137], v[16:17], v[160:161], v[136:137]
	v_pk_fma_f32 v[196:197], v[24:25], v[220:221], v[196:197]
	v_pk_fma_f32 v[138:139], v[18:19], v[162:163], v[138:139]
	v_pk_fma_f32 v[198:199], v[26:27], v[222:223], v[198:199]
	v_pk_fma_f32 v[140:141], v[20:21], v[164:165], v[140:141]
	v_pk_fma_f32 v[200:201], v[28:29], v[224:225], v[200:201]
	v_pk_fma_f32 v[142:143], v[22:23], v[166:167], v[142:143]
	v_pk_fma_f32 v[202:203], v[30:31], v[226:227], v[202:203]
	v_pk_fma_f32 v[136:137], v[32:33], v[168:169], v[136:137]
	v_pk_fma_f32 v[196:197], v[40:41], v[228:229], v[196:197]
	v_pk_fma_f32 v[138:139], v[34:35], v[170:171], v[138:139]
	v_pk_fma_f32 v[198:199], v[42:43], v[230:231], v[198:199]
	v_pk_fma_f32 v[140:141], v[36:37], v[172:173], v[140:141]
	v_pk_fma_f32 v[200:201], v[44:45], v[232:233], v[200:201]
	v_pk_fma_f32 v[142:143], v[38:39], v[174:175], v[142:143]
	v_pk_fma_f32 v[202:203], v[46:47], v[234:235], v[202:203]
	v_pk_mul_f32 v[184:185], v[136:137], v[180:181]
	v_pk_mul_f32 v[186:187], v[138:139], v[180:181]
	v_pk_mul_f32 v[188:189], v[140:141], v[180:181]
	v_pk_mul_f32 v[190:191], v[142:143], v[180:181]
	v_exp_f32_e32 v184, v184
	v_exp_f32_e32 v185, v185
	v_exp_f32_e32 v186, v186
	v_exp_f32_e32 v187, v187
	v_exp_f32_e32 v188, v188
	v_exp_f32_e32 v189, v189
	v_exp_f32_e32 v190, v190
	v_exp_f32_e32 v191, v191
	s_nop 0
	v_pk_add_f32 v[184:185], v[184:185], v[144:145]
	v_pk_add_f32 v[186:187], v[186:187], v[144:145]
	v_pk_add_f32 v[188:189], v[188:189], v[144:145]
	v_pk_add_f32 v[190:191], v[190:191], v[144:145]
	v_rcp_f32_e32 v184, v184
	v_rcp_f32_e32 v185, v185
	v_rcp_f32_e32 v186, v186
	v_rcp_f32_e32 v187, v187
	v_rcp_f32_e32 v188, v188
	v_rcp_f32_e32 v189, v189
	v_rcp_f32_e32 v190, v190
	v_rcp_f32_e32 v191, v191
	s_nop 0
	v_pk_mul_f32 v[136:137], v[136:137], v[184:185]
	v_pk_mul_f32 v[138:139], v[138:139], v[186:187]
	v_pk_mul_f32 v[140:141], v[140:141], v[188:189]
	v_pk_mul_f32 v[142:143], v[142:143], v[190:191]
	v_pk_mul_f32 v[136:137], v[136:137], v[196:197]
	v_pk_mul_f32 v[138:139], v[138:139], v[198:199]
	v_pk_mul_f32 v[140:141], v[140:141], v[200:201]
	v_pk_mul_f32 v[142:143], v[142:143], v[202:203]
	v_cvt_pk_bf16_f32 v12, v136, v137
	v_cvt_pk_bf16_f32 v13, v138, v139
	v_cvt_pk_bf16_f32 v14, v140, v141
	v_cvt_pk_bf16_f32 v15, v142, v143
	global_store_dwordx4 v6, v[12:15], s[36:37]
	v_add_u32_e32 v6, 5632, v6
	s_waitcnt vmcnt(25)
	v_lshlrev_b32_e32 v48, 16, v80
	v_and_b32_e32 v49, s99, v80
	v_lshlrev_b32_e32 v50, 16, v81
	v_and_b32_e32 v51, s99, v81
	v_lshlrev_b32_e32 v52, 16, v82
	v_and_b32_e32 v53, s99, v82
	v_lshlrev_b32_e32 v54, 16, v83
	v_and_b32_e32 v55, s99, v83
	v_lshlrev_b32_e32 v56, 16, v84
	v_and_b32_e32 v57, s99, v84
	v_lshlrev_b32_e32 v58, 16, v85
	v_and_b32_e32 v59, s99, v85
	v_lshlrev_b32_e32 v60, 16, v86
	v_and_b32_e32 v61, s99, v86
	v_lshlrev_b32_e32 v62, 16, v87
	v_and_b32_e32 v63, s99, v87
	v_add_u32_e32 v10, 67073792, v5
	global_load_dwordx4 v[80:83], v10, s[2:3] offset:-2816
	global_load_dwordx4 v[84:87], v10, s[2:3] offset:2816
	v_pk_fma_f32 v[136:137], v[16:17], v[152:153], v[236:237]
	v_pk_fma_f32 v[196:197], v[24:25], v[212:213], v[244:245]
	v_pk_fma_f32 v[138:139], v[18:19], v[154:155], v[238:239]
	v_pk_fma_f32 v[198:199], v[26:27], v[214:215], v[246:247]
	v_pk_fma_f32 v[140:141], v[20:21], v[156:157], v[240:241]
	v_pk_fma_f32 v[200:201], v[28:29], v[216:217], v[248:249]
	v_pk_fma_f32 v[142:143], v[22:23], v[158:159], v[242:243]
	v_pk_fma_f32 v[202:203], v[30:31], v[218:219], v[250:251]
	v_pk_fma_f32 v[136:137], v[32:33], v[160:161], v[136:137]
	v_pk_fma_f32 v[196:197], v[40:41], v[220:221], v[196:197]
	v_pk_fma_f32 v[138:139], v[34:35], v[162:163], v[138:139]
	v_pk_fma_f32 v[198:199], v[42:43], v[222:223], v[198:199]
	v_pk_fma_f32 v[140:141], v[36:37], v[164:165], v[140:141]
	v_pk_fma_f32 v[200:201], v[44:45], v[224:225], v[200:201]
	v_pk_fma_f32 v[142:143], v[38:39], v[166:167], v[142:143]
	v_pk_fma_f32 v[202:203], v[46:47], v[226:227], v[202:203]
	v_pk_fma_f32 v[136:137], v[48:49], v[168:169], v[136:137]
	v_pk_fma_f32 v[196:197], v[56:57], v[228:229], v[196:197]
	v_pk_fma_f32 v[138:139], v[50:51], v[170:171], v[138:139]
	v_pk_fma_f32 v[198:199], v[58:59], v[230:231], v[198:199]
	v_pk_fma_f32 v[140:141], v[52:53], v[172:173], v[140:141]
	v_pk_fma_f32 v[200:201], v[60:61], v[232:233], v[200:201]
	v_pk_fma_f32 v[142:143], v[54:55], v[174:175], v[142:143]
	v_pk_fma_f32 v[202:203], v[62:63], v[234:235], v[202:203]
	v_pk_mul_f32 v[184:185], v[136:137], v[180:181]
	v_pk_mul_f32 v[186:187], v[138:139], v[180:181]
	v_pk_mul_f32 v[188:189], v[140:141], v[180:181]
	v_pk_mul_f32 v[190:191], v[142:143], v[180:181]
	v_exp_f32_e32 v184, v184
	v_exp_f32_e32 v185, v185
	v_exp_f32_e32 v186, v186
	v_exp_f32_e32 v187, v187
	v_exp_f32_e32 v188, v188
	v_exp_f32_e32 v189, v189
	v_exp_f32_e32 v190, v190
	v_exp_f32_e32 v191, v191
	s_nop 0
	v_pk_add_f32 v[184:185], v[184:185], v[144:145]
	v_pk_add_f32 v[186:187], v[186:187], v[144:145]
	v_pk_add_f32 v[188:189], v[188:189], v[144:145]
	v_pk_add_f32 v[190:191], v[190:191], v[144:145]
	v_rcp_f32_e32 v184, v184
	v_rcp_f32_e32 v185, v185
	v_rcp_f32_e32 v186, v186
	v_rcp_f32_e32 v187, v187
	v_rcp_f32_e32 v188, v188
	v_rcp_f32_e32 v189, v189
	v_rcp_f32_e32 v190, v190
	v_rcp_f32_e32 v191, v191
	s_nop 0
	v_pk_mul_f32 v[136:137], v[136:137], v[184:185]
	v_pk_mul_f32 v[138:139], v[138:139], v[186:187]
	v_pk_mul_f32 v[140:141], v[140:141], v[188:189]
	v_pk_mul_f32 v[142:143], v[142:143], v[190:191]
	v_pk_mul_f32 v[136:137], v[136:137], v[196:197]
	v_pk_mul_f32 v[138:139], v[138:139], v[198:199]
	v_pk_mul_f32 v[140:141], v[140:141], v[200:201]
	v_pk_mul_f32 v[142:143], v[142:143], v[202:203]
	v_cvt_pk_bf16_f32 v12, v136, v137
	v_cvt_pk_bf16_f32 v13, v138, v139
	v_cvt_pk_bf16_f32 v14, v140, v141
	v_cvt_pk_bf16_f32 v15, v142, v143
	global_store_dwordx4 v6, v[12:15], s[36:37]
	v_add_u32_e32 v6, 5632, v6
	s_waitcnt vmcnt(25)
; __device__ __forceinline__ unsigned cvt_pk_bf16(float lo, float hi) { unsigned r; asm volatile("v_cvt_pk_bf16_f32 %0, %1, %2" : "=v"(r) : "v"(lo), "v"(hi)); return r; }
; __device__ __forceinline__ float silu_f(float x) { return x * __builtin_amdgcn_rcpf(1.0f + __builtin_amdgcn_exp2f(-LOG2E * x)); }
; __device__ __forceinline__ float bflo(unsigned w) { return __uint_as_float(w << 16); }
; __device__ __forceinline__ float bfhi(unsigned w) { return __uint_as_float(w & 0xffff0000u); }
; __device__ __forceinline__ void conv_phase(const bf16_t* Z, bf16_t* UA, const float* cw, const float* cb, int nrows, int rowoff) {
;     ...
;         for (int rr = 0; rr < 16; ++rr) {
;             u32x4 na = zero, ng = zero; if (rr < 15 || has_right) { na = *(const u32x4*)(zp + (size_t)(rr + 1) * FFN2); ng = *(const u32x4*)(zp + (size_t)(rr + 1) * FFN2 + FFN); }
;             u32x4 o;
; #pragma unroll
;             for (int e2 = 0; e2 < 4; ++e2) {
;                 const float a0 = bflo(pa[e2]) * wa[0][2 * e2] + bflo(ca[e2]) * wa[1][2 * e2] + bflo(na[e2]) * wa[2][2 * e2] + ba[2 * e2];
;                 const float a1 = bfhi(pa[e2]) * wa[0][2 * e2 + 1] + bfhi(ca[e2]) * wa[1][2 * e2 + 1] + bfhi(na[e2]) * wa[2][2 * e2 + 1] + ba[2 * e2 + 1];
;                 const float g0 = bflo(pg[e2]) * wg[0][2 * e2] + bflo(cgv[e2]) * wg[1][2 * e2] + bflo(ng[e2]) * wg[2][2 * e2] + bg[2 * e2];
;                 const float g1 = bfhi(pg[e2]) * wg[0][2 * e2 + 1] + bfhi(cgv[e2]) * wg[1][2 * e2 + 1] + bfhi(ng[e2]) * wg[2][2 * e2 + 1] + bg[2 * e2 + 1];
;                 o[e2] = cvt_pk_bf16(silu_f(a0) * g0, silu_f(a1) * g1); }
;             *(u32x4*)(UA + (size_t)(r0 + rr) * FFN + c0) = o;
;             pa = ca; pg = cgv; ca = na; cgv = ng;
	v_lshlrev_b32_e32 v16, 16, v88
	v_and_b32_e32 v17, s99, v88
	v_lshlrev_b32_e32 v18, 16, v89
	v_and_b32_e32 v19, s99, v89
	v_lshlrev_b32_e32 v20, 16, v90
	v_and_b32_e32 v21, s99, v90
	v_lshlrev_b32_e32 v22, 16, v91
	v_and_b32_e32 v23, s99, v91
	v_lshlrev_b32_e32 v24, 16, v92
	v_and_b32_e32 v25, s99, v92
	v_lshlrev_b32_e32 v26, 16, v93
	v_and_b32_e32 v27, s99, v93
	v_lshlrev_b32_e32 v28, 16, v94
	v_and_b32_e32 v29, s99, v94
	v_lshlrev_b32_e32 v30, 16, v95
	v_and_b32_e32 v31, s99, v95
	v_add_u32_e32 v11, 67085056, v5
	global_load_dwordx4 v[88:91], v11, s[2:3] offset:-2816
	global_load_dwordx4 v[92:95], v11, s[2:3] offset:2816
	v_pk_fma_f32 v[136:137], v[32:33], v[152:153], v[236:237]
	v_pk_fma_f32 v[196:197], v[40:41], v[212:213], v[244:245]
	v_pk_fma_f32 v[138:139], v[34:35], v[154:155], v[238:239]
	v_pk_fma_f32 v[198:199], v[42:43], v[214:215], v[246:247]
	v_pk_fma_f32 v[140:141], v[36:37], v[156:157], v[240:241]
	v_pk_fma_f32 v[200:201], v[44:45], v[216:217], v[248:249]
	v_pk_fma_f32 v[142:143], v[38:39], v[158:159], v[242:243]
	v_pk_fma_f32 v[202:203], v[46:47], v[218:219], v[250:251]
	v_pk_fma_f32 v[136:137], v[48:49], v[160:161], v[136:137]
	v_pk_fma_f32 v[196:197], v[56:57], v[220:221], v[196:197]
	v_pk_fma_f32 v[138:139], v[50:51], v[162:163], v[138:139]
	v_pk_fma_f32 v[198:199], v[58:59], v[222:223], v[198:199]
	v_pk_fma_f32 v[140:141], v[52:53], v[164:165], v[140:141]
	v_pk_fma_f32 v[200:201], v[60:61], v[224:225], v[200:201]
	v_pk_fma_f32 v[142:143], v[54:55], v[166:167], v[142:143]
	v_pk_fma_f32 v[202:203], v[62:63], v[226:227], v[202:203]
	v_pk_fma_f32 v[136:137], v[16:17], v[168:169], v[136:137]
	v_pk_fma_f32 v[196:197], v[24:25], v[228:229], v[196:197]
	v_pk_fma_f32 v[138:139], v[18:19], v[170:171], v[138:139]
	v_pk_fma_f32 v[198:199], v[26:27], v[230:231], v[198:199]
	v_pk_fma_f32 v[140:141], v[20:21], v[172:173], v[140:141]
	v_pk_fma_f32 v[200:201], v[28:29], v[232:233], v[200:201]
	v_pk_fma_f32 v[142:143], v[22:23], v[174:175], v[142:143]
	v_pk_fma_f32 v[202:203], v[30:31], v[234:235], v[202:203]
	v_pk_mul_f32 v[184:185], v[136:137], v[180:181]
	v_pk_mul_f32 v[186:187], v[138:139], v[180:181]
	v_pk_mul_f32 v[188:189], v[140:141], v[180:181]
	v_pk_mul_f32 v[190:191], v[142:143], v[180:181]
	v_exp_f32_e32 v184, v184
	v_exp_f32_e32 v185, v185
	v_exp_f32_e32 v186, v186
	v_exp_f32_e32 v187, v187
	v_exp_f32_e32 v188, v188
	v_exp_f32_e32 v189, v189
	v_exp_f32_e32 v190, v190
	v_exp_f32_e32 v191, v191
	s_nop 0
	v_pk_add_f32 v[184:185], v[184:185], v[144:145]
	v_pk_add_f32 v[186:187], v[186:187], v[144:145]
	v_pk_add_f32 v[188:189], v[188:189], v[144:145]
	v_pk_add_f32 v[190:191], v[190:191], v[144:145]
	v_rcp_f32_e32 v184, v184
	v_rcp_f32_e32 v185, v185
	v_rcp_f32_e32 v186, v186
	v_rcp_f32_e32 v187, v187
	v_rcp_f32_e32 v188, v188
	v_rcp_f32_e32 v189, v189
	v_rcp_f32_e32 v190, v190
	v_rcp_f32_e32 v191, v191
	s_nop 0
	v_pk_mul_f32 v[136:137], v[136:137], v[184:185]
	v_pk_mul_f32 v[138:139], v[138:139], v[186:187]
	v_pk_mul_f32 v[140:141], v[140:141], v[188:189]
	v_pk_mul_f32 v[142:143], v[142:143], v[190:191]
	v_pk_mul_f32 v[136:137], v[136:137], v[196:197]
	v_pk_mul_f32 v[138:139], v[138:139], v[198:199]
	v_pk_mul_f32 v[140:141], v[140:141], v[200:201]
	v_pk_mul_f32 v[142:143], v[142:143], v[202:203]
	v_cvt_pk_bf16_f32 v12, v136, v137
	v_cvt_pk_bf16_f32 v13, v138, v139
	v_cvt_pk_bf16_f32 v14, v140, v141
	v_cvt_pk_bf16_f32 v15, v142, v143
	global_store_dwordx4 v6, v[12:15], s[36:37]
	v_add_u32_e32 v6, 5632, v6
	s_waitcnt vmcnt(25)
	v_lshlrev_b32_e32 v32, 16, v96
	v_and_b32_e32 v33, s99, v96
	v_lshlrev_b32_e32 v34, 16, v97
	v_and_b32_e32 v35, s99, v97
	v_lshlrev_b32_e32 v36, 16, v98
	v_and_b32_e32 v37, s99, v98
	v_lshlrev_b32_e32 v38, 16, v99
	v_and_b32_e32 v39, s99, v99
	v_lshlrev_b32_e32 v40, 16, v100
	v_and_b32_e32 v41, s99, v100
	v_lshlrev_b32_e32 v42, 16, v101
	v_and_b32_e32 v43, s99, v101
	v_lshlrev_b32_e32 v44, 16, v102
	v_and_b32_e32 v45, s99, v102
	v_lshlrev_b32_e32 v46, 16, v103
	v_and_b32_e32 v47, s99, v103
	v_add_u32_e32 v10, 67096320, v5
	global_load_dwordx4 v[96:99], v10, s[2:3] offset:-2816
	global_load_dwordx4 v[100:103], v10, s[2:3] offset:2816
	v_pk_fma_f32 v[136:137], v[48:49], v[152:153], v[236:237]
	v_pk_fma_f32 v[196:197], v[56:57], v[212:213], v[244:245]
	v_pk_fma_f32 v[138:139], v[50:51], v[154:155], v[238:239]
	v_pk_fma_f32 v[198:199], v[58:59], v[214:215], v[246:247]
	v_pk_fma_f32 v[140:141], v[52:53], v[156:157], v[240:241]
	v_pk_fma_f32 v[200:201], v[60:61], v[216:217], v[248:249]
	v_pk_fma_f32 v[142:143], v[54:55], v[158:159], v[242:243]
	v_pk_fma_f32 v[202:203], v[62:63], v[218:219], v[250:251]
	v_pk_fma_f32 v[136:137], v[16:17], v[160:161], v[136:137]
	v_pk_fma_f32 v[196:197], v[24:25], v[220:221], v[196:197]
	v_pk_fma_f32 v[138:139], v[18:19], v[162:163], v[138:139]
	v_pk_fma_f32 v[198:199], v[26:27], v[222:223], v[198:199]
	v_pk_fma_f32 v[140:141], v[20:21], v[164:165], v[140:141]
	v_pk_fma_f32 v[200:201], v[28:29], v[224:225], v[200:201]
	v_pk_fma_f32 v[142:143], v[22:23], v[166:167], v[142:143]
	v_pk_fma_f32 v[202:203], v[30:31], v[226:227], v[202:203]
	v_pk_fma_f32 v[136:137], v[32:33], v[168:169], v[136:137]
	v_pk_fma_f32 v[196:197], v[40:41], v[228:229], v[196:197]
	v_pk_fma_f32 v[138:139], v[34:35], v[170:171], v[138:139]
	v_pk_fma_f32 v[198:199], v[42:43], v[230:231], v[198:199]
	v_pk_fma_f32 v[140:141], v[36:37], v[172:173], v[140:141]
	v_pk_fma_f32 v[200:201], v[44:45], v[232:233], v[200:201]
	v_pk_fma_f32 v[142:143], v[38:39], v[174:175], v[142:143]
	v_pk_fma_f32 v[202:203], v[46:47], v[234:235], v[202:203]
	v_pk_mul_f32 v[184:185], v[136:137], v[180:181]
	v_pk_mul_f32 v[186:187], v[138:139], v[180:181]
	v_pk_mul_f32 v[188:189], v[140:141], v[180:181]
	v_pk_mul_f32 v[190:191], v[142:143], v[180:181]
	v_exp_f32_e32 v184, v184
	v_exp_f32_e32 v185, v185
	v_exp_f32_e32 v186, v186
	v_exp_f32_e32 v187, v187
	v_exp_f32_e32 v188, v188
	v_exp_f32_e32 v189, v189
	v_exp_f32_e32 v190, v190
	v_exp_f32_e32 v191, v191
	s_nop 0
	v_pk_add_f32 v[184:185], v[184:185], v[144:145]
	v_pk_add_f32 v[186:187], v[186:187], v[144:145]
	v_pk_add_f32 v[188:189], v[188:189], v[144:145]
	v_pk_add_f32 v[190:191], v[190:191], v[144:145]
	v_rcp_f32_e32 v184, v184
	v_rcp_f32_e32 v185, v185
	v_rcp_f32_e32 v186, v186
	v_rcp_f32_e32 v187, v187
	v_rcp_f32_e32 v188, v188
	v_rcp_f32_e32 v189, v189
	v_rcp_f32_e32 v190, v190
	v_rcp_f32_e32 v191, v191
	s_nop 0
	v_pk_mul_f32 v[136:137], v[136:137], v[184:185]
	v_pk_mul_f32 v[138:139], v[138:139], v[186:187]
	v_pk_mul_f32 v[140:141], v[140:141], v[188:189]
	v_pk_mul_f32 v[142:143], v[142:143], v[190:191]
	v_pk_mul_f32 v[136:137], v[136:137], v[196:197]
	v_pk_mul_f32 v[138:139], v[138:139], v[198:199]
	v_pk_mul_f32 v[140:141], v[140:141], v[200:201]
	v_pk_mul_f32 v[142:143], v[142:143], v[202:203]
	v_cvt_pk_bf16_f32 v12, v136, v137
	v_cvt_pk_bf16_f32 v13, v138, v139
	v_cvt_pk_bf16_f32 v14, v140, v141
	v_cvt_pk_bf16_f32 v15, v142, v143
	global_store_dwordx4 v6, v[12:15], s[36:37]
	v_add_u32_e32 v6, 5632, v6
	s_waitcnt vmcnt(25)
; __device__ __forceinline__ unsigned cvt_pk_bf16(float lo, float hi) { unsigned r; asm volatile("v_cvt_pk_bf16_f32 %0, %1, %2" : "=v"(r) : "v"(lo), "v"(hi)); return r; }
; __device__ __forceinline__ float silu_f(float x) { return x * __builtin_amdgcn_rcpf(1.0f + __builtin_amdgcn_exp2f(-LOG2E * x)); }
; __device__ __forceinline__ float bflo(unsigned w) { return __uint_as_float(w << 16); }
; __device__ __forceinline__ float bfhi(unsigned w) { return __uint_as_float(w & 0xffff0000u); }
; __device__ __forceinline__ void conv_phase(const bf16_t* Z, bf16_t* UA, const float* cw, const float* cb, int nrows, int rowoff) {
;     ...
;         for (int rr = 0; rr < 16; ++rr) {
;             u32x4 na = zero, ng = zero; if (rr < 15 || has_right) { na = *(const u32x4*)(zp + (size_t)(rr + 1) * FFN2); ng = *(const u32x4*)(zp + (size_t)(rr + 1) * FFN2 + FFN); }
;             u32x4 o;
; #pragma unroll
;             for (int e2 = 0; e2 < 4; ++e2) {
;                 const float a0 = bflo(pa[e2]) * wa[0][2 * e2] + bflo(ca[e2]) * wa[1][2 * e2] + bflo(na[e2]) * wa[2][2 * e2] + ba[2 * e2];
;                 const float a1 = bfhi(pa[e2]) * wa[0][2 * e2 + 1] + bfhi(ca[e2]) * wa[1][2 * e2 + 1] + bfhi(na[e2]) * wa[2][2 * e2 + 1] + ba[2 * e2 + 1];
;                 const float g0 = bflo(pg[e2]) * wg[0][2 * e2] + bflo(cgv[e2]) * wg[1][2 * e2] + bflo(ng[e2]) * wg[2][2 * e2] + bg[2 * e2];
;                 const float g1 = bfhi(pg[e2]) * wg[0][2 * e2 + 1] + bfhi(cgv[e2]) * wg[1][2 * e2 + 1] + bfhi(ng[e2]) * wg[2][2 * e2 + 1] + bg[2 * e2 + 1];
;                 o[e2] = cvt_pk_bf16(silu_f(a0) * g0, silu_f(a1) * g1); }
;             *(u32x4*)(UA + (size_t)(r0 + rr) * FFN + c0) = o;
;             pa = ca; pg = cgv; ca = na; cgv = ng;
	v_lshlrev_b32_e32 v48, 16, v104
	v_and_b32_e32 v49, s99, v104
	v_lshlrev_b32_e32 v50, 16, v105
	v_and_b32_e32 v51, s99, v105
	v_lshlrev_b32_e32 v52, 16, v106
	v_and_b32_e32 v53, s99, v106
	v_lshlrev_b32_e32 v54, 16, v107
	v_and_b32_e32 v55, s99, v107
	v_lshlrev_b32_e32 v56, 16, v108
	v_and_b32_e32 v57, s99, v108
	v_lshlrev_b32_e32 v58, 16, v109
	v_and_b32_e32 v59, s99, v109
	v_lshlrev_b32_e32 v60, 16, v110
	v_and_b32_e32 v61, s99, v110
	v_lshlrev_b32_e32 v62, 16, v111
	v_and_b32_e32 v63, s99, v111
	v_add_u32_e32 v11, 67107584, v5
	global_load_dwordx4 v[104:107], v11, s[2:3] offset:-2816
	global_load_dwordx4 v[108:111], v11, s[2:3] offset:2816
	v_pk_fma_f32 v[136:137], v[16:17], v[152:153], v[236:237]
	v_pk_fma_f32 v[196:197], v[24:25], v[212:213], v[244:245]
	v_pk_fma_f32 v[138:139], v[18:19], v[154:155], v[238:239]
	v_pk_fma_f32 v[198:199], v[26:27], v[214:215], v[246:247]
	v_pk_fma_f32 v[140:141], v[20:21], v[156:157], v[240:241]
	v_pk_fma_f32 v[200:201], v[28:29], v[216:217], v[248:249]
	v_pk_fma_f32 v[142:143], v[22:23], v[158:159], v[242:243]
	v_pk_fma_f32 v[202:203], v[30:31], v[218:219], v[250:251]
	v_pk_fma_f32 v[136:137], v[32:33], v[160:161], v[136:137]
	v_pk_fma_f32 v[196:197], v[40:41], v[220:221], v[196:197]
	v_pk_fma_f32 v[138:139], v[34:35], v[162:163], v[138:139]
	v_pk_fma_f32 v[198:199], v[42:43], v[222:223], v[198:199]
	v_pk_fma_f32 v[140:141], v[36:37], v[164:165], v[140:141]
	v_pk_fma_f32 v[200:201], v[44:45], v[224:225], v[200:201]
	v_pk_fma_f32 v[142:143], v[38:39], v[166:167], v[142:143]
	v_pk_fma_f32 v[202:203], v[46:47], v[226:227], v[202:203]
	v_pk_fma_f32 v[136:137], v[48:49], v[168:169], v[136:137]
	v_pk_fma_f32 v[196:197], v[56:57], v[228:229], v[196:197]
	v_pk_fma_f32 v[138:139], v[50:51], v[170:171], v[138:139]
	v_pk_fma_f32 v[198:199], v[58:59], v[230:231], v[198:199]
	v_pk_fma_f32 v[140:141], v[52:53], v[172:173], v[140:141]
	v_pk_fma_f32 v[200:201], v[60:61], v[232:233], v[200:201]
	v_pk_fma_f32 v[142:143], v[54:55], v[174:175], v[142:143]
	v_pk_fma_f32 v[202:203], v[62:63], v[234:235], v[202:203]
	v_pk_mul_f32 v[184:185], v[136:137], v[180:181]
	v_pk_mul_f32 v[186:187], v[138:139], v[180:181]
	v_pk_mul_f32 v[188:189], v[140:141], v[180:181]
	v_pk_mul_f32 v[190:191], v[142:143], v[180:181]
	v_exp_f32_e32 v184, v184
	v_exp_f32_e32 v185, v185
	v_exp_f32_e32 v186, v186
	v_exp_f32_e32 v187, v187
	v_exp_f32_e32 v188, v188
	v_exp_f32_e32 v189, v189
	v_exp_f32_e32 v190, v190
	v_exp_f32_e32 v191, v191
	s_nop 0
	v_pk_add_f32 v[184:185], v[184:185], v[144:145]
	v_pk_add_f32 v[186:187], v[186:187], v[144:145]
	v_pk_add_f32 v[188:189], v[188:189], v[144:145]
	v_pk_add_f32 v[190:191], v[190:191], v[144:145]
	v_rcp_f32_e32 v184, v184
	v_rcp_f32_e32 v185, v185
	v_rcp_f32_e32 v186, v186
	v_rcp_f32_e32 v187, v187
	v_rcp_f32_e32 v188, v188
	v_rcp_f32_e32 v189, v189
	v_rcp_f32_e32 v190, v190
	v_rcp_f32_e32 v191, v191
	s_nop 0
	v_pk_mul_f32 v[136:137], v[136:137], v[184:185]
	v_pk_mul_f32 v[138:139], v[138:139], v[186:187]
	v_pk_mul_f32 v[140:141], v[140:141], v[188:189]
	v_pk_mul_f32 v[142:143], v[142:143], v[190:191]
	v_pk_mul_f32 v[136:137], v[136:137], v[196:197]
	v_pk_mul_f32 v[138:139], v[138:139], v[198:199]
	v_pk_mul_f32 v[140:141], v[140:141], v[200:201]
	v_pk_mul_f32 v[142:143], v[142:143], v[202:203]
	v_cvt_pk_bf16_f32 v12, v136, v137
	v_cvt_pk_bf16_f32 v13, v138, v139
	v_cvt_pk_bf16_f32 v14, v140, v141
	v_cvt_pk_bf16_f32 v15, v142, v143
	global_store_dwordx4 v6, v[12:15], s[36:37]
	v_add_u32_e32 v6, 5632, v6
	s_waitcnt vmcnt(25)
	v_lshlrev_b32_e32 v16, 16, v112
	v_and_b32_e32 v17, s99, v112
	v_lshlrev_b32_e32 v18, 16, v113
	v_and_b32_e32 v19, s99, v113
	v_lshlrev_b32_e32 v20, 16, v114
	v_and_b32_e32 v21, s99, v114
	v_lshlrev_b32_e32 v22, 16, v115
	v_and_b32_e32 v23, s99, v115
	v_lshlrev_b32_e32 v24, 16, v116
	v_and_b32_e32 v25, s99, v116
	v_lshlrev_b32_e32 v26, 16, v117
	v_and_b32_e32 v27, s99, v117
	v_lshlrev_b32_e32 v28, 16, v118
	v_and_b32_e32 v29, s99, v118
	v_lshlrev_b32_e32 v30, 16, v119
	v_and_b32_e32 v31, s99, v119
	v_add_u32_e32 v10, 67118848, v5
	global_load_dwordx4 v[112:115], v10, s[2:3] offset:-2816
	global_load_dwordx4 v[116:119], v10, s[2:3] offset:2816
	v_pk_fma_f32 v[136:137], v[32:33], v[152:153], v[236:237]
	v_pk_fma_f32 v[196:197], v[40:41], v[212:213], v[244:245]
	v_pk_fma_f32 v[138:139], v[34:35], v[154:155], v[238:239]
	v_pk_fma_f32 v[198:199], v[42:43], v[214:215], v[246:247]
	v_pk_fma_f32 v[140:141], v[36:37], v[156:157], v[240:241]
	v_pk_fma_f32 v[200:201], v[44:45], v[216:217], v[248:249]
	v_pk_fma_f32 v[142:143], v[38:39], v[158:159], v[242:243]
	v_pk_fma_f32 v[202:203], v[46:47], v[218:219], v[250:251]
	v_pk_fma_f32 v[136:137], v[48:49], v[160:161], v[136:137]
	v_pk_fma_f32 v[196:197], v[56:57], v[220:221], v[196:197]
	v_pk_fma_f32 v[138:139], v[50:51], v[162:163], v[138:139]
	v_pk_fma_f32 v[198:199], v[58:59], v[222:223], v[198:199]
	v_pk_fma_f32 v[140:141], v[52:53], v[164:165], v[140:141]
	v_pk_fma_f32 v[200:201], v[60:61], v[224:225], v[200:201]
	v_pk_fma_f32 v[142:143], v[54:55], v[166:167], v[142:143]
	v_pk_fma_f32 v[202:203], v[62:63], v[226:227], v[202:203]
	v_pk_fma_f32 v[136:137], v[16:17], v[168:169], v[136:137]
	v_pk_fma_f32 v[196:197], v[24:25], v[228:229], v[196:197]
	v_pk_fma_f32 v[138:139], v[18:19], v[170:171], v[138:139]
	v_pk_fma_f32 v[198:199], v[26:27], v[230:231], v[198:199]
	v_pk_fma_f32 v[140:141], v[20:21], v[172:173], v[140:141]
	v_pk_fma_f32 v[200:201], v[28:29], v[232:233], v[200:201]
	v_pk_fma_f32 v[142:143], v[22:23], v[174:175], v[142:143]
	v_pk_fma_f32 v[202:203], v[30:31], v[234:235], v[202:203]
	v_pk_mul_f32 v[184:185], v[136:137], v[180:181]
	v_pk_mul_f32 v[186:187], v[138:139], v[180:181]
	v_pk_mul_f32 v[188:189], v[140:141], v[180:181]
	v_pk_mul_f32 v[190:191], v[142:143], v[180:181]
	v_exp_f32_e32 v184, v184
	v_exp_f32_e32 v185, v185
	v_exp_f32_e32 v186, v186
	v_exp_f32_e32 v187, v187
	v_exp_f32_e32 v188, v188
	v_exp_f32_e32 v189, v189
	v_exp_f32_e32 v190, v190
	v_exp_f32_e32 v191, v191
	s_nop 0
	v_pk_add_f32 v[184:185], v[184:185], v[144:145]
	v_pk_add_f32 v[186:187], v[186:187], v[144:145]
	v_pk_add_f32 v[188:189], v[188:189], v[144:145]
	v_pk_add_f32 v[190:191], v[190:191], v[144:145]
	v_rcp_f32_e32 v184, v184
	v_rcp_f32_e32 v185, v185
	v_rcp_f32_e32 v186, v186
	v_rcp_f32_e32 v187, v187
	v_rcp_f32_e32 v188, v188
	v_rcp_f32_e32 v189, v189
	v_rcp_f32_e32 v190, v190
	v_rcp_f32_e32 v191, v191
	s_nop 0
	v_pk_mul_f32 v[136:137], v[136:137], v[184:185]
	v_pk_mul_f32 v[138:139], v[138:139], v[186:187]
	v_pk_mul_f32 v[140:141], v[140:141], v[188:189]
	v_pk_mul_f32 v[142:143], v[142:143], v[190:191]
	v_pk_mul_f32 v[136:137], v[136:137], v[196:197]
	v_pk_mul_f32 v[138:139], v[138:139], v[198:199]
	v_pk_mul_f32 v[140:141], v[140:141], v[200:201]
	v_pk_mul_f32 v[142:143], v[142:143], v[202:203]
	v_cvt_pk_bf16_f32 v12, v136, v137
	v_cvt_pk_bf16_f32 v13, v138, v139
	v_cvt_pk_bf16_f32 v14, v140, v141
	v_cvt_pk_bf16_f32 v15, v142, v143
	global_store_dwordx4 v6, v[12:15], s[36:37]
	v_add_u32_e32 v6, 5632, v6
	s_waitcnt vmcnt(25)
; __device__ __forceinline__ unsigned cvt_pk_bf16(float lo, float hi) { unsigned r; asm volatile("v_cvt_pk_bf16_f32 %0, %1, %2" : "=v"(r) : "v"(lo), "v"(hi)); return r; }
; __device__ __forceinline__ float silu_f(float x) { return x * __builtin_amdgcn_rcpf(1.0f + __builtin_amdgcn_exp2f(-LOG2E * x)); }
; __device__ __forceinline__ float bflo(unsigned w) { return __uint_as_float(w << 16); }
; __device__ __forceinline__ float bfhi(unsigned w) { return __uint_as_float(w & 0xffff0000u); }
; __device__ __forceinline__ void conv_phase(const bf16_t* Z, bf16_t* UA, const float* cw, const float* cb, int nrows, int rowoff) {
;     ...
;         for (int rr = 0; rr < 16; ++rr) {
;             u32x4 na = zero, ng = zero; if (rr < 15 || has_right) { na = *(const u32x4*)(zp + (size_t)(rr + 1) * FFN2); ng = *(const u32x4*)(zp + (size_t)(rr + 1) * FFN2 + FFN); }
;             u32x4 o;
; #pragma unroll
;             for (int e2 = 0; e2 < 4; ++e2) {
;                 const float a0 = bflo(pa[e2]) * wa[0][2 * e2] + bflo(ca[e2]) * wa[1][2 * e2] + bflo(na[e2]) * wa[2][2 * e2] + ba[2 * e2];
;                 const float a1 = bfhi(pa[e2]) * wa[0][2 * e2 + 1] + bfhi(ca[e2]) * wa[1][2 * e2 + 1] + bfhi(na[e2]) * wa[2][2 * e2 + 1] + ba[2 * e2 + 1];
;                 const float g0 = bflo(pg[e2]) * wg[0][2 * e2] + bflo(cgv[e2]) * wg[1][2 * e2] + bflo(ng[e2]) * wg[2][2 * e2] + bg[2 * e2];
;                 const float g1 = bfhi(pg[e2]) * wg[0][2 * e2 + 1] + bfhi(cgv[e2]) * wg[1][2 * e2 + 1] + bfhi(ng[e2]) * wg[2][2 * e2 + 1] + bg[2 * e2 + 1];
;                 o[e2] = cvt_pk_bf16(silu_f(a0) * g0, silu_f(a1) * g1); }
;             *(u32x4*)(UA + (size_t)(r0 + rr) * FFN + c0) = o;
;             pa = ca; pg = cgv; ca = na; cgv = ng;
	v_lshlrev_b32_e32 v32, 16, v120
	v_and_b32_e32 v33, s99, v120
	v_lshlrev_b32_e32 v34, 16, v121
	v_and_b32_e32 v35, s99, v121
	v_lshlrev_b32_e32 v36, 16, v122
	v_and_b32_e32 v37, s99, v122
	v_lshlrev_b32_e32 v38, 16, v123
	v_and_b32_e32 v39, s99, v123
	v_lshlrev_b32_e32 v40, 16, v124
	v_and_b32_e32 v41, s99, v124
	v_lshlrev_b32_e32 v42, 16, v125
	v_and_b32_e32 v43, s99, v125
	v_lshlrev_b32_e32 v44, 16, v126
	v_and_b32_e32 v45, s99, v126
	v_lshlrev_b32_e32 v46, 16, v127
	v_and_b32_e32 v47, s99, v127
	v_add_u32_e32 v11, 67130112, v5
	global_load_dwordx4 v[120:123], v11, s[2:3] offset:-2816
	global_load_dwordx4 v[124:127], v11, s[2:3] offset:2816
	v_pk_fma_f32 v[136:137], v[48:49], v[152:153], v[236:237]
	v_pk_fma_f32 v[196:197], v[56:57], v[212:213], v[244:245]
	v_pk_fma_f32 v[138:139], v[50:51], v[154:155], v[238:239]
	v_pk_fma_f32 v[198:199], v[58:59], v[214:215], v[246:247]
	v_pk_fma_f32 v[140:141], v[52:53], v[156:157], v[240:241]
	v_pk_fma_f32 v[200:201], v[60:61], v[216:217], v[248:249]
	v_pk_fma_f32 v[142:143], v[54:55], v[158:159], v[242:243]
	v_pk_fma_f32 v[202:203], v[62:63], v[218:219], v[250:251]
	v_pk_fma_f32 v[136:137], v[16:17], v[160:161], v[136:137]
	v_pk_fma_f32 v[196:197], v[24:25], v[220:221], v[196:197]
	v_pk_fma_f32 v[138:139], v[18:19], v[162:163], v[138:139]
	v_pk_fma_f32 v[198:199], v[26:27], v[222:223], v[198:199]
	v_pk_fma_f32 v[140:141], v[20:21], v[164:165], v[140:141]
	v_pk_fma_f32 v[200:201], v[28:29], v[224:225], v[200:201]
	v_pk_fma_f32 v[142:143], v[22:23], v[166:167], v[142:143]
	v_pk_fma_f32 v[202:203], v[30:31], v[226:227], v[202:203]
	v_pk_fma_f32 v[136:137], v[32:33], v[168:169], v[136:137]
	v_pk_fma_f32 v[196:197], v[40:41], v[228:229], v[196:197]
	v_pk_fma_f32 v[138:139], v[34:35], v[170:171], v[138:139]
	v_pk_fma_f32 v[198:199], v[42:43], v[230:231], v[198:199]
	v_pk_fma_f32 v[140:141], v[36:37], v[172:173], v[140:141]
	v_pk_fma_f32 v[200:201], v[44:45], v[232:233], v[200:201]
	v_pk_fma_f32 v[142:143], v[38:39], v[174:175], v[142:143]
	v_pk_fma_f32 v[202:203], v[46:47], v[234:235], v[202:203]
	v_pk_mul_f32 v[184:185], v[136:137], v[180:181]
	v_pk_mul_f32 v[186:187], v[138:139], v[180:181]
	v_pk_mul_f32 v[188:189], v[140:141], v[180:181]
	v_pk_mul_f32 v[190:191], v[142:143], v[180:181]
	v_exp_f32_e32 v184, v184
	v_exp_f32_e32 v185, v185
	v_exp_f32_e32 v186, v186
	v_exp_f32_e32 v187, v187
	v_exp_f32_e32 v188, v188
	v_exp_f32_e32 v189, v189
	v_exp_f32_e32 v190, v190
	v_exp_f32_e32 v191, v191
	s_nop 0
	v_pk_add_f32 v[184:185], v[184:185], v[144:145]
	v_pk_add_f32 v[186:187], v[186:187], v[144:145]
	v_pk_add_f32 v[188:189], v[188:189], v[144:145]
	v_pk_add_f32 v[190:191], v[190:191], v[144:145]
	v_rcp_f32_e32 v184, v184
	v_rcp_f32_e32 v185, v185
	v_rcp_f32_e32 v186, v186
	v_rcp_f32_e32 v187, v187
	v_rcp_f32_e32 v188, v188
	v_rcp_f32_e32 v189, v189
	v_rcp_f32_e32 v190, v190
	v_rcp_f32_e32 v191, v191
	s_nop 0
	v_pk_mul_f32 v[136:137], v[136:137], v[184:185]
	v_pk_mul_f32 v[138:139], v[138:139], v[186:187]
	v_pk_mul_f32 v[140:141], v[140:141], v[188:189]
	v_pk_mul_f32 v[142:143], v[142:143], v[190:191]
	v_pk_mul_f32 v[136:137], v[136:137], v[196:197]
	v_pk_mul_f32 v[138:139], v[138:139], v[198:199]
	v_pk_mul_f32 v[140:141], v[140:141], v[200:201]
	v_pk_mul_f32 v[142:143], v[142:143], v[202:203]
	v_cvt_pk_bf16_f32 v12, v136, v137
	v_cvt_pk_bf16_f32 v13, v138, v139
	v_cvt_pk_bf16_f32 v14, v140, v141
	v_cvt_pk_bf16_f32 v15, v142, v143
	global_store_dwordx4 v6, v[12:15], s[36:37]
	v_add_u32_e32 v6, 5632, v6
	s_waitcnt vmcnt(25)
; __device__ __forceinline__ unsigned cvt_pk_bf16(float lo, float hi) { unsigned r; asm volatile("v_cvt_pk_bf16_f32 %0, %1, %2" : "=v"(r) : "v"(lo), "v"(hi)); return r; }
; __device__ __forceinline__ float silu_f(float x) { return x * __builtin_amdgcn_rcpf(1.0f + __builtin_amdgcn_exp2f(-LOG2E * x)); }
; __device__ __forceinline__ float bflo(unsigned w) { return __uint_as_float(w << 16); }
; __device__ __forceinline__ float bfhi(unsigned w) { return __uint_as_float(w & 0xffff0000u); }
; __device__ __forceinline__ void conv_phase(const bf16_t* Z, bf16_t* UA, const float* cw, const float* cb, int nrows, int rowoff) {
;     ...
;         for (int rr = 0; rr < 16; ++rr) {
;             u32x4 na = zero, ng = zero; if (rr < 15 || has_right) { na = *(const u32x4*)(zp + (size_t)(rr + 1) * FFN2); ng = *(const u32x4*)(zp + (size_t)(rr + 1) * FFN2 + FFN); }
;             u32x4 o;
; #pragma unroll
;             for (int e2 = 0; e2 < 4; ++e2) {
;                 const float a0 = bflo(pa[e2]) * wa[0][2 * e2] + bflo(ca[e2]) * wa[1][2 * e2] + bflo(na[e2]) * wa[2][2 * e2] + ba[2 * e2];
;                 const float a1 = bfhi(pa[e2]) * wa[0][2 * e2 + 1] + bfhi(ca[e2]) * wa[1][2 * e2 + 1] + bfhi(na[e2]) * wa[2][2 * e2 + 1] + ba[2 * e2 + 1];
;                 const float g0 = bflo(pg[e2]) * wg[0][2 * e2] + bflo(cgv[e2]) * wg[1][2 * e2] + bflo(ng[e2]) * wg[2][2 * e2] + bg[2 * e2];
;                 const float g1 = bfhi(pg[e2]) * wg[0][2 * e2 + 1] + bfhi(cgv[e2]) * wg[1][2 * e2 + 1] + bfhi(ng[e2]) * wg[2][2 * e2 + 1] + bg[2 * e2 + 1];
;                 o[e2] = cvt_pk_bf16(silu_f(a0) * g0, silu_f(a1) * g1); }
;             *(u32x4*)(UA + (size_t)(r0 + rr) * FFN + c0) = o;
;             pa = ca; pg = cgv; ca = na; cgv = ng;
;         }
; __device__ __forceinline__ void xcd_barrier(const XcdBarrier& b) {
;     asm volatile("s_waitcnt vmcnt(0)" ::: "memory");
;     __syncthreads();
;     if (threadIdx.x == 0) {
;         unsigned* bar = b.bar;
;         __builtin_amdgcn_s_waitcnt(0);
;         unsigned nloc = b.st[0], nx = b.st[1];
;         if (nloc == 0u) { xcd_barrier_complete(bar, b.x, nloc, nx); b.st[0] = nloc; b.st[1] = nx; }
	v_cndmask_b32_e64 v128, 0, v128, s[100:101]
	v_cndmask_b32_e64 v129, 0, v129, s[100:101]
	v_cndmask_b32_e64 v130, 0, v130, s[100:101]
	v_cndmask_b32_e64 v131, 0, v131, s[100:101]
	v_cndmask_b32_e64 v132, 0, v132, s[100:101]
	v_cndmask_b32_e64 v133, 0, v133, s[100:101]
	v_cndmask_b32_e64 v134, 0, v134, s[100:101]
	v_cndmask_b32_e64 v135, 0, v135, s[100:101]
	v_lshlrev_b32_e32 v48, 16, v128
	v_and_b32_e32 v49, s99, v128
	v_lshlrev_b32_e32 v50, 16, v129
	v_and_b32_e32 v51, s99, v129
	v_lshlrev_b32_e32 v52, 16, v130
	v_and_b32_e32 v53, s99, v130
	v_lshlrev_b32_e32 v54, 16, v131
	v_and_b32_e32 v55, s99, v131
	v_lshlrev_b32_e32 v56, 16, v132
	v_and_b32_e32 v57, s99, v132
	v_lshlrev_b32_e32 v58, 16, v133
	v_and_b32_e32 v59, s99, v133
	v_lshlrev_b32_e32 v60, 16, v134
	v_and_b32_e32 v61, s99, v134
	v_lshlrev_b32_e32 v62, 16, v135
	v_and_b32_e32 v63, s99, v135
	v_add_u32_e32 v10, 67141376, v5
	global_load_dwordx4 v[128:131], v10, s[2:3] offset:-2816
	global_load_dwordx4 v[132:135], v10, s[2:3] offset:2816
	v_pk_fma_f32 v[136:137], v[16:17], v[152:153], v[236:237]
	v_pk_fma_f32 v[196:197], v[24:25], v[212:213], v[244:245]
	v_pk_fma_f32 v[138:139], v[18:19], v[154:155], v[238:239]
	v_pk_fma_f32 v[198:199], v[26:27], v[214:215], v[246:247]
	v_pk_fma_f32 v[140:141], v[20:21], v[156:157], v[240:241]
	v_pk_fma_f32 v[200:201], v[28:29], v[216:217], v[248:249]
	v_pk_fma_f32 v[142:143], v[22:23], v[158:159], v[242:243]
	v_pk_fma_f32 v[202:203], v[30:31], v[218:219], v[250:251]
	v_pk_fma_f32 v[136:137], v[32:33], v[160:161], v[136:137]
	v_pk_fma_f32 v[196:197], v[40:41], v[220:221], v[196:197]
	v_pk_fma_f32 v[138:139], v[34:35], v[162:163], v[138:139]
	v_pk_fma_f32 v[198:199], v[42:43], v[222:223], v[198:199]
	v_pk_fma_f32 v[140:141], v[36:37], v[164:165], v[140:141]
	v_pk_fma_f32 v[200:201], v[44:45], v[224:225], v[200:201]
	v_pk_fma_f32 v[142:143], v[38:39], v[166:167], v[142:143]
	v_pk_fma_f32 v[202:203], v[46:47], v[226:227], v[202:203]
	v_pk_fma_f32 v[136:137], v[48:49], v[168:169], v[136:137]
	v_pk_fma_f32 v[196:197], v[56:57], v[228:229], v[196:197]
	v_pk_fma_f32 v[138:139], v[50:51], v[170:171], v[138:139]
	v_pk_fma_f32 v[198:199], v[58:59], v[230:231], v[198:199]
	v_pk_fma_f32 v[140:141], v[52:53], v[172:173], v[140:141]
	v_pk_fma_f32 v[200:201], v[60:61], v[232:233], v[200:201]
	v_pk_fma_f32 v[142:143], v[54:55], v[174:175], v[142:143]
	v_pk_fma_f32 v[202:203], v[62:63], v[234:235], v[202:203]
	v_pk_mul_f32 v[184:185], v[136:137], v[180:181]
	v_pk_mul_f32 v[186:187], v[138:139], v[180:181]
	v_pk_mul_f32 v[188:189], v[140:141], v[180:181]
	v_pk_mul_f32 v[190:191], v[142:143], v[180:181]
	v_exp_f32_e32 v184, v184
	v_exp_f32_e32 v185, v185
	v_exp_f32_e32 v186, v186
	v_exp_f32_e32 v187, v187
	v_exp_f32_e32 v188, v188
	v_exp_f32_e32 v189, v189
	v_exp_f32_e32 v190, v190
	v_exp_f32_e32 v191, v191
	s_nop 0
	v_pk_add_f32 v[184:185], v[184:185], v[144:145]
	v_pk_add_f32 v[186:187], v[186:187], v[144:145]
	v_pk_add_f32 v[188:189], v[188:189], v[144:145]
	v_pk_add_f32 v[190:191], v[190:191], v[144:145]
	v_rcp_f32_e32 v184, v184
	v_rcp_f32_e32 v185, v185
	v_rcp_f32_e32 v186, v186
	v_rcp_f32_e32 v187, v187
	v_rcp_f32_e32 v188, v188
	v_rcp_f32_e32 v189, v189
	v_rcp_f32_e32 v190, v190
	v_rcp_f32_e32 v191, v191
	s_nop 0
	v_pk_mul_f32 v[136:137], v[136:137], v[184:185]
	v_pk_mul_f32 v[138:139], v[138:139], v[186:187]
	v_pk_mul_f32 v[140:141], v[140:141], v[188:189]
	v_pk_mul_f32 v[142:143], v[142:143], v[190:191]
	v_pk_mul_f32 v[136:137], v[136:137], v[196:197]
	v_pk_mul_f32 v[138:139], v[138:139], v[198:199]
	v_pk_mul_f32 v[140:141], v[140:141], v[200:201]
	v_pk_mul_f32 v[142:143], v[142:143], v[202:203]
	v_cvt_pk_bf16_f32 v12, v136, v137
	v_cvt_pk_bf16_f32 v13, v138, v139
	v_cvt_pk_bf16_f32 v14, v140, v141
	v_cvt_pk_bf16_f32 v15, v142, v143
	global_store_dwordx4 v6, v[12:15], s[36:37]
	v_add_u32_e32 v5, 67043328, v5
	v_add_u32_e32 v6, 33437184, v6
	v_add_u32_e32 v7, 372, v7
	s_add_u32 s98, s98, 1
	s_cmp_lt_u32 s98, 6
	s_cbranch_scc1 .Lconv_item_l0
	s_waitcnt vmcnt(0)
	s_barrier
	s_mov_b64 s[2:3], exec
	v_readlane_b32 s12, v254, 0
	v_readlane_b32 s13, v254, 1
	s_and_b64 s[12:13], s[2:3], s[12:13]
	s_mov_b64 exec, s[12:13]
	s_cbranch_execz .LBB0_516
	v_readlane_b32 s12, v255, 22
	s_waitcnt vmcnt(0) expcnt(0) lgkmcnt(0)
	s_nop 0
	v_mov_b32_e32 v1, s12
	ds_read_b32 v3, v1
	v_readlane_b32 s12, v255, 23
	s_waitcnt lgkmcnt(0)
	v_cmp_ne_u32_e32 vcc, 0, v3
	v_mov_b32_e32 v1, s12
	ds_read_b32 v2, v1
	s_cbranch_vccnz .LBB0_484
	s_mov_b32 s30, 1
	s_branch .LBB0_472
